# GEMM epilogue cross-row reductions (EpiResidNorm P7/P10, EpiP1): ds_bpermute xor-16/xor-32 round trips replaced by v_permlane16_swap / v_permlane32_swap (64 sites, bit-identical)
# baseline (speedup 1.0000x reference)
;     __device__ __forceinline__ void operator()(const f32x4 (&acc)[2][2][4][2], const Unit& u, int wr, int wc, int fr, int fq) const {
;     ...
;                     for (int bj = 0; bj < 2; ++bj) { const f32x4 a0 = acc[ai][bj][m][0], a1 = acc[ai][bj][m][1];
;                         float v = (a0[0] * a0[0] + a0[1] * a0[1]) + (a0[2] * a0[2] + a0[3] * a0[3]) + (a1[0] * a1[0] + a1[1] * a1[1]) + (a1[2] * a1[2] + a1[3] * a1[3]);
;                         v += __shfl_xor(v, 16); v += __shfl_xor(v, 32);
;                         if (fq == 0) xch[((((wr * 2 + ai) * 4 + m) * 16 + fr) * 2 + bj) * 4 + wc] = v; }
.LBB0_161:
	s_cmp_lt_u32 s27, 8
	s_cselect_b32 s5, s9, s11
	s_cselect_b32 s4, s8, s10
	v_lshlrev_b32_e32 v134, 2, v148
	global_load_dwordx4 v[130:133], v134, s[4:5] offset:16
	s_nop 0
	global_load_dwordx4 v[134:137], v134, s[4:5]
	v_mul_f32_e32 v177, v127, v127
	v_mul_f32_e32 v178, v129, v129
	v_fmac_f32_e32 v177, v126, v126
	v_fmac_f32_e32 v178, v128, v128
	v_and_b32_e32 v176, 64, v175
	v_add_f32_e32 v177, v177, v178
	v_mul_f32_e32 v178, v123, v123
	v_xor_b32_e32 v146, 16, v175
	v_add_u32_e32 v176, 64, v176
	v_fmac_f32_e32 v178, v122, v122
	v_cmp_lt_i32_e32 vcc, v146, v176
	v_add_f32_e32 v177, v177, v178
	v_mul_f32_e32 v178, v125, v125
	v_cndmask_b32_e32 v146, v175, v146, vcc
	v_fmac_f32_e32 v178, v124, v124
	v_lshlrev_b32_e32 v146, 2, v146
	v_add_f32_e32 v178, v178, v177
	v_mov_b32_e32 v179, v178
	s_nop 1
	v_permlane16_swap_b32_e32 v179, v178
	v_xor_b32_e32 v177, 32, v175
	v_cmp_lt_i32_e32 vcc, v177, v176
	s_waitcnt lgkmcnt(0)
	v_add_f32_e32 v178, v178, v179
	v_cndmask_b32_e32 v176, v175, v177, vcc
	v_lshlrev_b32_e32 v177, 2, v176
	v_mov_b32_e32 v179, v178
	s_nop 1
	v_permlane32_swap_b32_e32 v179, v178
	v_add_u32_e32 v176, s58, v161
	s_and_saveexec_b64 s[4:5], s[0:1]
	s_cbranch_execz .LBB0_163
	s_waitcnt lgkmcnt(0)
	v_add_f32_e32 v178, v178, v179
	ds_write_b32 v176, v178
.LBB0_163:
	s_or_b64 exec, exec, s[4:5]
	v_mul_f32_e32 v178, v119, v119
	s_waitcnt lgkmcnt(0)
	v_mul_f32_e32 v179, v121, v121
	v_fmac_f32_e32 v178, v118, v118
	v_fmac_f32_e32 v179, v120, v120
	v_add_f32_e32 v178, v178, v179
	v_mul_f32_e32 v179, v115, v115
	v_fmac_f32_e32 v179, v114, v114
	v_add_f32_e32 v178, v178, v179
	v_mul_f32_e32 v179, v117, v117
	v_fmac_f32_e32 v179, v116, v116
	v_add_f32_e32 v178, v179, v178
	v_mov_b32_e32 v179, v178
	s_nop 1
	v_permlane16_swap_b32_e32 v179, v178
	s_waitcnt lgkmcnt(0)
	v_add_f32_e32 v178, v178, v179
	v_mov_b32_e32 v179, v178
	s_nop 1
	v_permlane32_swap_b32_e32 v179, v178
	s_and_saveexec_b64 s[4:5], s[0:1]
	s_cbranch_execz .LBB0_165
	s_waitcnt lgkmcnt(0)
	v_add_f32_e32 v178, v178, v179
	ds_write_b32 v176, v178 offset:16
.LBB0_165:
	s_or_b64 exec, exec, s[4:5]
	v_mul_f32_e32 v178, v111, v111
	s_waitcnt lgkmcnt(0)
	v_mul_f32_e32 v179, v113, v113
	v_fmac_f32_e32 v178, v110, v110
	v_fmac_f32_e32 v179, v112, v112
	v_add_f32_e32 v178, v178, v179
	v_mul_f32_e32 v179, v107, v107
	v_fmac_f32_e32 v179, v106, v106
	v_add_f32_e32 v178, v178, v179
	v_mul_f32_e32 v179, v109, v109
	v_fmac_f32_e32 v179, v108, v108
	v_add_f32_e32 v178, v179, v178
	v_mov_b32_e32 v179, v178
	s_nop 1
	v_permlane16_swap_b32_e32 v179, v178
	s_waitcnt lgkmcnt(0)
	v_add_f32_e32 v178, v178, v179
	v_mov_b32_e32 v179, v178
	s_nop 1
	v_permlane32_swap_b32_e32 v179, v178
	s_and_saveexec_b64 s[4:5], s[0:1]
	s_cbranch_execz .LBB0_167
	s_waitcnt lgkmcnt(0)
	v_add_f32_e32 v178, v178, v179
	ds_write_b32 v176, v178 offset:512
.LBB0_167:
	s_or_b64 exec, exec, s[4:5]
	v_mul_f32_e32 v178, v103, v103
	s_waitcnt lgkmcnt(0)
	v_mul_f32_e32 v179, v105, v105
	v_fmac_f32_e32 v178, v102, v102
	v_fmac_f32_e32 v179, v104, v104
	v_add_f32_e32 v178, v178, v179
	v_mul_f32_e32 v179, v99, v99
	v_fmac_f32_e32 v179, v98, v98
	v_add_f32_e32 v178, v178, v179
	v_mul_f32_e32 v179, v101, v101
	v_fmac_f32_e32 v179, v100, v100
	v_add_f32_e32 v178, v179, v178
	v_mov_b32_e32 v179, v178
	s_nop 1
	v_permlane16_swap_b32_e32 v179, v178
	s_waitcnt lgkmcnt(0)
	v_add_f32_e32 v178, v178, v179
	v_mov_b32_e32 v179, v178
	s_nop 1
	v_permlane32_swap_b32_e32 v179, v178
	s_and_saveexec_b64 s[4:5], s[0:1]
	s_cbranch_execz .LBB0_169
	s_waitcnt lgkmcnt(0)
	v_add_f32_e32 v178, v178, v179
	ds_write_b32 v176, v178 offset:528
.LBB0_169:
	s_or_b64 exec, exec, s[4:5]
	v_mul_f32_e32 v178, v95, v95
	s_waitcnt lgkmcnt(0)
	v_mul_f32_e32 v179, v97, v97
	v_fmac_f32_e32 v178, v94, v94
	v_fmac_f32_e32 v179, v96, v96
	v_add_f32_e32 v178, v178, v179
	v_mul_f32_e32 v179, v91, v91
	v_fmac_f32_e32 v179, v90, v90
	v_add_f32_e32 v178, v178, v179
	v_mul_f32_e32 v179, v93, v93
	v_fmac_f32_e32 v179, v92, v92
	v_add_f32_e32 v178, v179, v178
	v_mov_b32_e32 v179, v178
	s_nop 1
	v_permlane16_swap_b32_e32 v179, v178
	s_waitcnt lgkmcnt(0)
	v_add_f32_e32 v178, v178, v179
	v_mov_b32_e32 v179, v178
	s_nop 1
	v_permlane32_swap_b32_e32 v179, v178
	s_and_saveexec_b64 s[4:5], s[0:1]
	s_cbranch_execz .LBB0_171
	s_waitcnt lgkmcnt(0)
	v_add_f32_e32 v178, v178, v179
	ds_write_b32 v176, v178 offset:1024
.LBB0_171:
	s_or_b64 exec, exec, s[4:5]
	v_mul_f32_e32 v178, v87, v87
	s_waitcnt lgkmcnt(0)
	v_mul_f32_e32 v179, v89, v89
	v_fmac_f32_e32 v178, v86, v86
	v_fmac_f32_e32 v179, v88, v88
	v_add_f32_e32 v178, v178, v179
	v_mul_f32_e32 v179, v83, v83
	v_fmac_f32_e32 v179, v82, v82
	v_add_f32_e32 v178, v178, v179
	v_mul_f32_e32 v179, v85, v85
	v_fmac_f32_e32 v179, v84, v84
	v_add_f32_e32 v178, v179, v178
	v_mov_b32_e32 v179, v178
	s_nop 1
	v_permlane16_swap_b32_e32 v179, v178
	s_waitcnt lgkmcnt(0)
	v_add_f32_e32 v178, v178, v179
	v_mov_b32_e32 v179, v178
	s_nop 1
	v_permlane32_swap_b32_e32 v179, v178
	s_and_saveexec_b64 s[4:5], s[0:1]
	s_cbranch_execz .LBB0_173
	s_waitcnt lgkmcnt(0)
	v_add_f32_e32 v178, v178, v179
	ds_write_b32 v176, v178 offset:1040
.LBB0_173:
	s_or_b64 exec, exec, s[4:5]
	v_mul_f32_e32 v178, v79, v79
	s_waitcnt lgkmcnt(0)
	v_mul_f32_e32 v179, v81, v81
	v_fmac_f32_e32 v178, v78, v78
	v_fmac_f32_e32 v179, v80, v80
	v_add_f32_e32 v178, v178, v179
	v_mul_f32_e32 v179, v75, v75
	v_fmac_f32_e32 v179, v74, v74
	v_add_f32_e32 v178, v178, v179
	v_mul_f32_e32 v179, v77, v77
	v_fmac_f32_e32 v179, v76, v76
	v_add_f32_e32 v178, v179, v178
	v_mov_b32_e32 v179, v178
	s_nop 1
	v_permlane16_swap_b32_e32 v179, v178
	s_waitcnt lgkmcnt(0)
	v_add_f32_e32 v178, v178, v179
	v_mov_b32_e32 v179, v178
	s_nop 1
	v_permlane32_swap_b32_e32 v179, v178
	s_and_saveexec_b64 s[4:5], s[0:1]
	s_cbranch_execz .LBB0_175
	s_waitcnt lgkmcnt(0)
	v_add_f32_e32 v178, v178, v179
	ds_write_b32 v176, v178 offset:1536
;     __device__ __forceinline__ void operator()(const f32x4 (&acc)[2][2][4][2], const Unit& u, int wr, int wc, int fr, int fq) const {
;     ...
;                     for (int bj = 0; bj < 2; ++bj) { const f32x4 a0 = acc[ai][bj][m][0], a1 = acc[ai][bj][m][1];
;                         float v = (a0[0] * a0[0] + a0[1] * a0[1]) + (a0[2] * a0[2] + a0[3] * a0[3]) + (a1[0] * a1[0] + a1[1] * a1[1]) + (a1[2] * a1[2] + a1[3] * a1[3]);
;                         v += __shfl_xor(v, 16); v += __shfl_xor(v, 32);
;                         if (fq == 0) xch[((((wr * 2 + ai) * 4 + m) * 16 + fr) * 2 + bj) * 4 + wc] = v; }
.LBB0_175:
	s_or_b64 exec, exec, s[4:5]
	v_mul_f32_e32 v178, v71, v71
	s_waitcnt lgkmcnt(0)
	v_mul_f32_e32 v179, v73, v73
	v_fmac_f32_e32 v178, v70, v70
	v_fmac_f32_e32 v179, v72, v72
	v_add_f32_e32 v178, v178, v179
	v_mul_f32_e32 v179, v67, v67
	v_fmac_f32_e32 v179, v66, v66
	v_add_f32_e32 v178, v178, v179
	v_mul_f32_e32 v179, v69, v69
	v_fmac_f32_e32 v179, v68, v68
	v_add_f32_e32 v178, v179, v178
	v_mov_b32_e32 v179, v178
	s_nop 1
	v_permlane16_swap_b32_e32 v179, v178
	s_waitcnt lgkmcnt(0)
	v_add_f32_e32 v178, v178, v179
	v_mov_b32_e32 v179, v178
	s_nop 1
	v_permlane32_swap_b32_e32 v179, v178
	s_and_saveexec_b64 s[4:5], s[0:1]
	s_cbranch_execz .LBB0_177
	s_waitcnt lgkmcnt(0)
	v_add_f32_e32 v178, v178, v179
	ds_write_b32 v176, v178 offset:1552
.LBB0_177:
	s_or_b64 exec, exec, s[4:5]
	v_mul_f32_e32 v178, v63, v63
	s_waitcnt lgkmcnt(0)
	v_mul_f32_e32 v179, v65, v65
	v_fmac_f32_e32 v178, v62, v62
	v_fmac_f32_e32 v179, v64, v64
	v_add_f32_e32 v178, v178, v179
	v_mul_f32_e32 v179, v59, v59
	v_fmac_f32_e32 v179, v58, v58
	v_add_f32_e32 v178, v178, v179
	v_mul_f32_e32 v179, v61, v61
	v_fmac_f32_e32 v179, v60, v60
	v_add_f32_e32 v178, v179, v178
	v_mov_b32_e32 v179, v178
	s_nop 1
	v_permlane16_swap_b32_e32 v179, v178
	s_waitcnt lgkmcnt(0)
	v_add_f32_e32 v178, v178, v179
	v_mov_b32_e32 v179, v178
	s_nop 1
	v_permlane32_swap_b32_e32 v179, v178
	s_and_saveexec_b64 s[4:5], s[0:1]
	s_cbranch_execz .LBB0_179
	s_waitcnt lgkmcnt(0)
	v_add_f32_e32 v178, v178, v179
	ds_write_b32 v176, v178 offset:2048
.LBB0_179:
	s_or_b64 exec, exec, s[4:5]
	v_mul_f32_e32 v178, v55, v55
	s_waitcnt lgkmcnt(0)
	v_mul_f32_e32 v179, v57, v57
	v_fmac_f32_e32 v178, v54, v54
	v_fmac_f32_e32 v179, v56, v56
	v_add_f32_e32 v178, v178, v179
	v_mul_f32_e32 v179, v51, v51
	v_fmac_f32_e32 v179, v50, v50
	v_add_f32_e32 v178, v178, v179
	v_mul_f32_e32 v179, v53, v53
	v_fmac_f32_e32 v179, v52, v52
	v_add_f32_e32 v178, v179, v178
	v_mov_b32_e32 v179, v178
	s_nop 1
	v_permlane16_swap_b32_e32 v179, v178
	s_waitcnt lgkmcnt(0)
	v_add_f32_e32 v178, v178, v179
	v_mov_b32_e32 v179, v178
	s_nop 1
	v_permlane32_swap_b32_e32 v179, v178
	s_and_saveexec_b64 s[4:5], s[0:1]
	s_cbranch_execz .LBB0_181
	s_waitcnt lgkmcnt(0)
	v_add_f32_e32 v178, v178, v179
	ds_write_b32 v176, v178 offset:2064
.LBB0_181:
	s_or_b64 exec, exec, s[4:5]
	v_mul_f32_e32 v178, v47, v47
	s_waitcnt lgkmcnt(0)
	v_mul_f32_e32 v179, v49, v49
	v_fmac_f32_e32 v178, v46, v46
	v_fmac_f32_e32 v179, v48, v48
	v_add_f32_e32 v178, v178, v179
	v_mul_f32_e32 v179, v43, v43
	v_fmac_f32_e32 v179, v42, v42
	v_add_f32_e32 v178, v178, v179
	v_mul_f32_e32 v179, v45, v45
	v_fmac_f32_e32 v179, v44, v44
	v_add_f32_e32 v178, v179, v178
	v_mov_b32_e32 v179, v178
	s_nop 1
	v_permlane16_swap_b32_e32 v179, v178
	s_waitcnt lgkmcnt(0)
	v_add_f32_e32 v178, v178, v179
	v_mov_b32_e32 v179, v178
	s_nop 1
	v_permlane32_swap_b32_e32 v179, v178
	s_and_saveexec_b64 s[4:5], s[0:1]
	s_cbranch_execz .LBB0_183
	s_waitcnt lgkmcnt(0)
	v_add_f32_e32 v178, v178, v179
	ds_write_b32 v176, v178 offset:2560
.LBB0_183:
	s_or_b64 exec, exec, s[4:5]
	v_mul_f32_e32 v178, v39, v39
	s_waitcnt lgkmcnt(0)
	v_mul_f32_e32 v179, v41, v41
	v_fmac_f32_e32 v178, v38, v38
	v_fmac_f32_e32 v179, v40, v40
	v_add_f32_e32 v178, v178, v179
	v_mul_f32_e32 v179, v35, v35
	v_fmac_f32_e32 v179, v34, v34
	v_add_f32_e32 v178, v178, v179
	v_mul_f32_e32 v179, v37, v37
	v_fmac_f32_e32 v179, v36, v36
	v_add_f32_e32 v178, v179, v178
	v_mov_b32_e32 v179, v178
	s_nop 1
	v_permlane16_swap_b32_e32 v179, v178
	s_waitcnt lgkmcnt(0)
	v_add_f32_e32 v178, v178, v179
	v_mov_b32_e32 v179, v178
	s_nop 1
	v_permlane32_swap_b32_e32 v179, v178
	s_and_saveexec_b64 s[4:5], s[0:1]
	s_cbranch_execz .LBB0_185
	s_waitcnt lgkmcnt(0)
	v_add_f32_e32 v178, v178, v179
	ds_write_b32 v176, v178 offset:2576
.LBB0_185:
	s_or_b64 exec, exec, s[4:5]
	v_mul_f32_e32 v178, v31, v31
	s_waitcnt lgkmcnt(0)
	v_mul_f32_e32 v179, v33, v33
	v_fmac_f32_e32 v178, v30, v30
	v_fmac_f32_e32 v179, v32, v32
	v_add_f32_e32 v178, v178, v179
	v_mul_f32_e32 v179, v27, v27
	v_fmac_f32_e32 v179, v26, v26
	v_add_f32_e32 v178, v178, v179
	v_mul_f32_e32 v179, v29, v29
	v_fmac_f32_e32 v179, v28, v28
	v_add_f32_e32 v178, v179, v178
	v_mov_b32_e32 v179, v178
	s_nop 1
	v_permlane16_swap_b32_e32 v179, v178
	s_waitcnt lgkmcnt(0)
	v_add_f32_e32 v178, v178, v179
	v_mov_b32_e32 v179, v178
	s_nop 1
	v_permlane32_swap_b32_e32 v179, v178
	s_and_saveexec_b64 s[4:5], s[0:1]
	s_cbranch_execz .LBB0_187
	s_waitcnt lgkmcnt(0)
	v_add_f32_e32 v178, v178, v179
	ds_write_b32 v176, v178 offset:3072
.LBB0_187:
	s_or_b64 exec, exec, s[4:5]
	v_mul_f32_e32 v178, v23, v23
	s_waitcnt lgkmcnt(0)
	v_mul_f32_e32 v179, v25, v25
	v_fmac_f32_e32 v178, v22, v22
	v_fmac_f32_e32 v179, v24, v24
	v_add_f32_e32 v178, v178, v179
	v_mul_f32_e32 v179, v19, v19
	v_fmac_f32_e32 v179, v18, v18
	v_add_f32_e32 v178, v178, v179
	v_mul_f32_e32 v179, v21, v21
	v_fmac_f32_e32 v179, v20, v20
	v_add_f32_e32 v178, v179, v178
	v_mov_b32_e32 v179, v178
	s_nop 1
	v_permlane16_swap_b32_e32 v179, v178
	s_waitcnt lgkmcnt(0)
	v_add_f32_e32 v178, v178, v179
	v_mov_b32_e32 v179, v178
	s_nop 1
	v_permlane32_swap_b32_e32 v179, v178
	s_and_saveexec_b64 s[4:5], s[0:1]
	s_cbranch_execz .LBB0_189
	s_waitcnt lgkmcnt(0)
	v_add_f32_e32 v178, v178, v179
	ds_write_b32 v176, v178 offset:3088
.LBB0_189:
	s_or_b64 exec, exec, s[4:5]
	v_mul_f32_e32 v178, v15, v15
	s_waitcnt lgkmcnt(0)
	v_mul_f32_e32 v179, v17, v17
	v_fmac_f32_e32 v178, v14, v14
	v_fmac_f32_e32 v179, v16, v16
	v_add_f32_e32 v178, v178, v179
	v_mul_f32_e32 v179, v11, v11
	v_fmac_f32_e32 v179, v10, v10
	v_add_f32_e32 v178, v178, v179
	v_mul_f32_e32 v179, v13, v13
	v_fmac_f32_e32 v179, v12, v12
	v_add_f32_e32 v178, v179, v178
	v_mov_b32_e32 v179, v178
	s_nop 1
	v_permlane16_swap_b32_e32 v179, v178
	s_waitcnt lgkmcnt(0)
	v_add_f32_e32 v178, v178, v179
	v_mov_b32_e32 v179, v178
	s_nop 1
	v_permlane32_swap_b32_e32 v179, v178
	s_and_saveexec_b64 s[4:5], s[0:1]
	s_cbranch_execz .LBB0_191
	s_waitcnt lgkmcnt(0)
	v_add_f32_e32 v178, v178, v179
	ds_write_b32 v176, v178 offset:3584
.LBB0_191:
	s_or_b64 exec, exec, s[4:5]
	v_mul_f32_e32 v178, v7, v7
	s_waitcnt lgkmcnt(0)
	v_mul_f32_e32 v179, v9, v9
	v_fmac_f32_e32 v178, v6, v6
	v_fmac_f32_e32 v179, v8, v8
	v_add_f32_e32 v178, v178, v179
	v_mul_f32_e32 v179, v3, v3
	v_fmac_f32_e32 v179, v2, v2
	v_add_f32_e32 v178, v178, v179
	v_mul_f32_e32 v179, v5, v5
	v_fmac_f32_e32 v179, v4, v4
	v_add_f32_e32 v178, v179, v178
	v_mov_b32_e32 v146, v178
	s_nop 1
	v_permlane16_swap_b32_e32 v146, v178
	s_waitcnt lgkmcnt(0)
	v_add_f32_e32 v146, v178, v146
	v_mov_b32_e32 v177, v146
	s_nop 1
	v_permlane32_swap_b32_e32 v177, v146
	s_and_saveexec_b64 s[4:5], s[0:1]
	s_cbranch_execz .LBB0_193
	s_waitcnt lgkmcnt(0)
	v_add_f32_e32 v146, v146, v177
	ds_write_b32 v176, v146 offset:3600

; __device__ __forceinline__ u32x4 pack8f(f32x4 a, f32x4 b) { u32x4 w; w.x = cvtpk(a[0], a[1]); w.y = cvtpk(a[2], a[3]); w.z = cvtpk(b[0], b[1]); w.w = cvtpk(b[2], b[3]); return w; }
;     __device__ __forceinline__ void operator()(const f32x4 (&acc)[2][2][4][2], const Unit& u, int wr, int wc, int fr, int fq) const {
;     ...
;             } else {
; #pragma unroll
;                 for (int m = 0; m < 4; ++m)
; #pragma unroll
;                     for (int bj = 0; bj < 2; ++bj) { const float* p = (const float*)base + (row0 + m * 16) * 4096 + col + bj * HALF; bq[m][bj][0] = __builtin_nontemporal_load((const f32x4*)p); bq[m][bj][1] = __builtin_nontemporal_load((const f32x4*)(p + 4)); }
;                 asm volatile("" ::: "memory");
;             }
; #pragma unroll
;             for (int m = 0; m < 4; ++m) { const size_t row = row0 + m * 16;
;                 float sq = 0.f;
; #pragma unroll
;                 for (int bj = 0; bj < 2; ++bj) { const size_t o = row * 4096 + col + bj * HALF;
;                     const f32x4 v0 = bq[m][bj][0] + acc[ai][bj][m][0], v1 = bq[m][bj][1] + acc[ai][bj][m][1];
;                     *(u32x4*)(xb + o) = pack8f(v0, v1);
;                     sq += (v0[0] * v0[0] + v0[1] * v0[1]) + (v0[2] * v0[2] + v0[3] * v0[3]) + (v1[0] * v1[0] + v1[1] * v1[1]) + (v1[2] * v1[2] + v1[3] * v1[3]); }
;                 sq += __shfl_xor(sq, 16); sq += __shfl_xor(sq, 32);
;                 if (fq == 0) atomicAdd(ss + row, sq); }
.LBB0_1642:
	v_lshl_or_b32 v194, s50, 8, v202
	v_lshl_add_u32 v198, s48, 8, v200
	v_ashrrev_i32_e32 v195, 31, v194
	v_ashrrev_i32_e32 v199, 31, v198
	v_lshl_add_u64 v[196:197], v[194:195], 2, s[14:15]
	v_lshlrev_b64 v[130:131], 14, v[198:199]
	v_lshl_add_u64 v[130:131], v[196:197], 0, v[130:131]
	global_load_dwordx4 v[208:211], v[130:131], off nt
	global_load_dwordx4 v[212:215], v[130:131], off offset:16 nt
	global_load_dwordx4 v[216:219], v[130:131], off offset:512 nt
	global_load_dwordx4 v[220:223], v[130:131], off offset:528 nt
	v_add_co_u32_e32 v134, vcc, s68, v130
	v_lshl_add_u64 v[132:133], v[130:131], 0, s[28:29]
	s_nop 0
	v_addc_co_u32_e32 v135, vcc, 0, v131, vcc
	v_add_co_u32_e32 v142, vcc, s69, v130
	v_lshl_add_u64 v[136:137], v[130:131], 0, s[30:31]
	s_nop 0
	v_addc_co_u32_e32 v143, vcc, 0, v131, vcc
	v_lshl_add_u64 v[138:139], v[130:131], 0, s[24:25]
	v_lshl_add_u64 v[140:141], v[130:131], 0, s[34:35]
	v_lshl_add_u64 v[224:225], v[130:131], 0, s[36:37]
	v_lshl_add_u64 v[226:227], v[130:131], 0, s[38:39]
	v_add_co_u32_e32 v130, vcc, s70, v130
	global_load_dwordx4 v[174:177], v[134:135], off nt
	global_load_dwordx4 v[170:173], v[132:133], off offset:16 nt
	global_load_dwordx4 v[166:169], v[134:135], off offset:512 nt
	global_load_dwordx4 v[162:165], v[136:137], off offset:16 nt
	v_addc_co_u32_e32 v131, vcc, 0, v131, vcc
	global_load_dwordx4 v[158:161], v[142:143], off nt
	global_load_dwordx4 v[154:157], v[138:139], off offset:16 nt
	global_load_dwordx4 v[150:153], v[142:143], off offset:512 nt
	global_load_dwordx4 v[146:149], v[140:141], off offset:16 nt
	s_nop 0
	global_load_dwordx4 v[142:145], v[130:131], off nt
	global_load_dwordx4 v[138:141], v[224:225], off offset:16 nt
	global_load_dwordx4 v[134:137], v[130:131], off offset:512 nt
	s_nop 0
	global_load_dwordx4 v[130:133], v[226:227], off offset:16 nt
	v_and_b32_e32 v224, 64, v206
	v_xor_b32_e32 v207, 16, v206
	v_add_u32_e32 v227, 64, v224
	v_cmp_lt_i32_e32 vcc, v207, v227
	v_xor_b32_e32 v226, 32, v206
	v_lshlrev_b64 v[224:225], 13, v[198:199]
	v_cndmask_b32_e32 v207, v206, v207, vcc
	v_lshlrev_b32_e32 v207, 2, v207
	v_cmp_lt_i32_e32 vcc, v226, v227
	v_lshl_add_u64 v[224:225], s[18:19], 0, v[224:225]
	v_lshl_add_u64 v[224:225], v[194:195], 1, v[224:225]
	v_cndmask_b32_e32 v226, v206, v226, vcc
	s_waitcnt vmcnt(0)
	v_pk_add_f32 v[128:129], v[128:129], v[210:211]
	v_pk_add_f32 v[126:127], v[126:127], v[208:209]
	v_pk_add_f32 v[120:121], v[120:121], v[218:219]
	v_pk_add_f32 v[118:119], v[118:119], v[216:217]
	v_pk_add_f32 v[122:123], v[122:123], v[212:213]
	v_pk_add_f32 v[208:209], v[116:117], v[222:223]
	v_pk_add_f32 v[210:211], v[114:115], v[220:221]
	v_mul_f32_e32 v116, v127, v127
	v_mul_f32_e32 v117, v129, v129
	v_mul_f32_e32 v212, v119, v119
	v_mul_f32_e32 v213, v121, v121
	v_pk_add_f32 v[124:125], v[124:125], v[214:215]
	v_cvt_pk_bf16_f32 v114, v126, v127
	v_mul_f32_e32 v127, v123, v123
	v_mul_f32_e32 v214, v211, v211
	v_fmac_f32_e32 v116, v126, v126
	v_fmac_f32_e32 v117, v128, v128
	v_fmac_f32_e32 v212, v118, v118
	v_fmac_f32_e32 v213, v120, v120
	v_cvt_pk_bf16_f32 v115, v128, v129
	v_mul_f32_e32 v129, v125, v125
	v_mul_f32_e32 v215, v209, v209
	v_fmac_f32_e32 v127, v122, v122
	v_fmac_f32_e32 v214, v210, v210
	v_add_f32_e32 v116, v116, v117
	v_add_f32_e32 v117, v212, v213
	v_fmac_f32_e32 v129, v124, v124
	v_fmac_f32_e32 v215, v208, v208
	v_add_f32_e32 v116, v116, v127
	v_add_f32_e32 v117, v117, v214
	v_add_f32_e32 v116, v129, v116
	v_add_f32_e32 v117, v215, v117
	v_add_f32_e32 v126, v116, v117
	v_mov_b32_e32 v127, v126
	s_nop 1
	v_permlane16_swap_b32_e32 v127, v126
	v_cvt_pk_bf16_f32 v116, v122, v123
	v_cvt_pk_bf16_f32 v117, v124, v125
	global_store_dwordx4 v[224:225], v[114:117], off
	v_cvt_pk_bf16_f32 v118, v118, v119
	v_cvt_pk_bf16_f32 v119, v120, v121
	v_cvt_pk_bf16_f32 v120, v210, v211
	v_cvt_pk_bf16_f32 v121, v208, v209
	global_store_dwordx4 v[224:225], v[118:121], off offset:256
	s_waitcnt lgkmcnt(0)
	v_add_f32_e32 v114, v126, v127
	v_lshlrev_b32_e32 v116, 2, v226
	v_mov_b32_e32 v115, v114
	s_nop 1
	v_permlane32_swap_b32_e32 v115, v114
	s_and_saveexec_b64 s[48:49], s[0:1]
	v_readlane_b32 s56, v254, 13
	v_readlane_b32 s74, v254, 17
	v_readlane_b32 s57, v254, 14
	s_cbranch_execz .LBB0_1644
	v_lshl_add_u64 v[118:119], v[198:199], 2, s[20:21]
	s_waitcnt lgkmcnt(0)
	v_add_f32_e32 v114, v114, v115
	global_atomic_add_f32 v[118:119], v114, off
.LBB0_1644:
	s_or_b64 exec, exec, s[48:49]
	v_pk_add_f32 v[110:111], v[110:111], v[174:175]
	v_pk_add_f32 v[112:113], v[112:113], v[176:177]
	v_pk_add_f32 v[122:123], v[106:107], v[170:171]
	v_cvt_pk_bf16_f32 v106, v110, v111
	v_mul_f32_e32 v111, v111, v111
	v_fmac_f32_e32 v111, v110, v110
	v_mul_f32_e32 v110, v113, v113
	v_fmac_f32_e32 v110, v112, v112
	v_add_f32_e32 v110, v111, v110
	v_mul_f32_e32 v111, v123, v123
	v_pk_add_f32 v[104:105], v[104:105], v[168:169]
	v_pk_add_f32 v[102:103], v[102:103], v[166:167]
	v_pk_add_f32 v[120:121], v[108:109], v[172:173]
	v_cvt_pk_bf16_f32 v107, v112, v113
	v_fmac_f32_e32 v111, v122, v122
	v_pk_add_f32 v[112:113], v[98:99], v[162:163]
	v_mul_f32_e32 v98, v103, v103
	v_mul_f32_e32 v99, v105, v105
	v_add_f32_e32 v110, v110, v111
	v_mul_f32_e32 v111, v121, v121
	v_fmac_f32_e32 v98, v102, v102
	v_fmac_f32_e32 v99, v104, v104
	v_fmac_f32_e32 v111, v120, v120
	v_add_f32_e32 v98, v98, v99
	v_mul_f32_e32 v99, v113, v113
	v_add_f32_e32 v117, v111, v110
	v_pk_add_f32 v[110:111], v[100:101], v[164:165]
	v_fmac_f32_e32 v99, v112, v112
	v_add_f32_e32 v98, v98, v99
	v_mul_f32_e32 v99, v111, v111
	v_fmac_f32_e32 v99, v110, v110
	v_add_f32_e32 v98, v99, v98
	v_add_f32_e32 v101, v117, v98
	v_mov_b32_e32 v117, v101
	s_nop 1
	v_permlane16_swap_b32_e32 v117, v101
	v_or_b32_e32 v114, 16, v198
	s_waitcnt lgkmcnt(1)
	v_mov_b32_e32 v115, v199
	v_lshlrev_b64 v[118:119], 13, v[114:115]
	v_lshl_add_u64 v[98:99], s[18:19], 0, v[118:119]
	v_lshl_add_u64 v[118:119], v[194:195], 1, v[98:99]
	s_waitcnt lgkmcnt(0)
	v_add_f32_e32 v98, v101, v117
	v_mov_b32_e32 v99, v98
	s_nop 1
	v_permlane32_swap_b32_e32 v99, v98
	v_cvt_pk_bf16_f32 v108, v122, v123
	v_cvt_pk_bf16_f32 v109, v120, v121
	global_store_dwordx4 v[118:119], v[106:109], off
	v_cvt_pk_bf16_f32 v100, v102, v103
	v_cvt_pk_bf16_f32 v101, v104, v105
	v_cvt_pk_bf16_f32 v102, v112, v113
	v_cvt_pk_bf16_f32 v103, v110, v111
	global_store_dwordx4 v[118:119], v[100:103], off offset:256
	s_and_saveexec_b64 s[48:49], s[0:1]
	s_cbranch_execz .LBB0_1646
	v_lshl_add_u64 v[100:101], v[114:115], 2, s[20:21]
	s_waitcnt lgkmcnt(0)
	v_add_f32_e32 v98, v98, v99
	global_atomic_add_f32 v[100:101], v98, off
; __device__ __forceinline__ u32x4 pack8f(f32x4 a, f32x4 b) { u32x4 w; w.x = cvtpk(a[0], a[1]); w.y = cvtpk(a[2], a[3]); w.z = cvtpk(b[0], b[1]); w.w = cvtpk(b[2], b[3]); return w; }
; __device__ __forceinline__ void unpack8f(u32x4 w, f32x4& a, f32x4& b) { a = (f32x4){bflo(w.x), bfhi(w.x), bflo(w.y), bfhi(w.y)}; b = (f32x4){bflo(w.z), bfhi(w.z), bflo(w.w), bfhi(w.w)}; }
;     __device__ __forceinline__ void operator()(const f32x4 (&acc)[2][2][4][2], const Unit& u, int wr, int wc, int fr, int fq) const {
;     ...
;             if (BASE_BF16) {
;                 u32x4 raw[4][2];
; #pragma unroll
;                 for (int m = 0; m < 4; ++m)
; #pragma unroll
;                     for (int bj = 0; bj < 2; ++bj) raw[m][bj] = __builtin_nontemporal_load((const u32x4*)((const bf16_t*)base + (row0 + m * 16) * 4096 + col + bj * HALF));
;                 asm volatile("" ::: "memory");
; #pragma unroll
;                 for (int m = 0; m < 4; ++m)
; #pragma unroll
;                     for (int bj = 0; bj < 2; ++bj) unpack8f(raw[m][bj], bq[m][bj][0], bq[m][bj][1]);
;             } else {
; #pragma unroll
;                 for (int m = 0; m < 4; ++m)
; #pragma unroll
;                     for (int bj = 0; bj < 2; ++bj) { const float* p = (const float*)base + (row0 + m * 16) * 4096 + col + bj * HALF; bq[m][bj][0] = __builtin_nontemporal_load((const f32x4*)p); bq[m][bj][1] = __builtin_nontemporal_load((const f32x4*)(p + 4)); }
;                 asm volatile("" ::: "memory");
;     ...
;             for (int m = 0; m < 4; ++m) { const size_t row = row0 + m * 16;
;                 float sq = 0.f;
; #pragma unroll
;                 for (int bj = 0; bj < 2; ++bj) { const size_t o = row * 4096 + col + bj * HALF;
;                     const f32x4 v0 = bq[m][bj][0] + acc[ai][bj][m][0], v1 = bq[m][bj][1] + acc[ai][bj][m][1];
;                     *(u32x4*)(xb + o) = pack8f(v0, v1);
;                     sq += (v0[0] * v0[0] + v0[1] * v0[1]) + (v0[2] * v0[2] + v0[3] * v0[3]) + (v1[0] * v1[0] + v1[1] * v1[1]) + (v1[2] * v1[2] + v1[3] * v1[3]); }
;                 sq += __shfl_xor(sq, 16); sq += __shfl_xor(sq, 32);
;                 if (fq == 0) atomicAdd(ss + row, sq); }
.LBB0_1646:
	s_or_b64 exec, exec, s[48:49]
	v_pk_add_f32 v[94:95], v[94:95], v[158:159]
	v_pk_add_f32 v[96:97], v[96:97], v[160:161]
	v_pk_add_f32 v[104:105], v[90:91], v[154:155]
	v_cvt_pk_bf16_f32 v90, v94, v95
	v_mul_f32_e32 v95, v95, v95
	v_fmac_f32_e32 v95, v94, v94
	v_mul_f32_e32 v94, v97, v97
	v_fmac_f32_e32 v94, v96, v96
	v_add_f32_e32 v94, v95, v94
	v_mul_f32_e32 v95, v105, v105
	v_pk_add_f32 v[88:89], v[88:89], v[152:153]
	v_pk_add_f32 v[86:87], v[86:87], v[150:151]
	v_pk_add_f32 v[102:103], v[92:93], v[156:157]
	v_cvt_pk_bf16_f32 v91, v96, v97
	v_fmac_f32_e32 v95, v104, v104
	v_pk_add_f32 v[96:97], v[82:83], v[146:147]
	v_mul_f32_e32 v82, v87, v87
	v_mul_f32_e32 v83, v89, v89
	v_add_f32_e32 v94, v94, v95
	v_mul_f32_e32 v95, v103, v103
	v_fmac_f32_e32 v82, v86, v86
	v_fmac_f32_e32 v83, v88, v88
	v_fmac_f32_e32 v95, v102, v102
	v_add_f32_e32 v82, v82, v83
	v_mul_f32_e32 v83, v97, v97
	v_cvt_pk_bf16_f32 v92, v104, v105
	v_cvt_pk_bf16_f32 v93, v102, v103
	v_add_f32_e32 v102, v95, v94
	v_pk_add_f32 v[94:95], v[84:85], v[148:149]
	v_fmac_f32_e32 v83, v96, v96
	v_add_f32_e32 v82, v82, v83
	v_mul_f32_e32 v83, v95, v95
	v_fmac_f32_e32 v83, v94, v94
	v_add_f32_e32 v82, v83, v82
	v_add_f32_e32 v85, v102, v82
	v_mov_b32_e32 v102, v85
	s_nop 1
	v_permlane16_swap_b32_e32 v102, v85
	v_or_b32_e32 v98, 32, v198
	s_waitcnt lgkmcnt(1)
	v_mov_b32_e32 v99, v199
	v_lshlrev_b64 v[100:101], 13, v[98:99]
	v_lshl_add_u64 v[82:83], s[18:19], 0, v[100:101]
	v_lshl_add_u64 v[100:101], v[194:195], 1, v[82:83]
	s_waitcnt lgkmcnt(0)
	v_add_f32_e32 v82, v85, v102
	v_mov_b32_e32 v83, v82
	s_nop 1
	v_permlane32_swap_b32_e32 v83, v82
	global_store_dwordx4 v[100:101], v[90:93], off
	v_cvt_pk_bf16_f32 v84, v86, v87
	v_cvt_pk_bf16_f32 v85, v88, v89
	v_cvt_pk_bf16_f32 v86, v96, v97
	v_cvt_pk_bf16_f32 v87, v94, v95
	global_store_dwordx4 v[100:101], v[84:87], off offset:256
	s_and_saveexec_b64 s[48:49], s[0:1]
	s_cbranch_execz .LBB0_1648
	v_lshl_add_u64 v[84:85], v[98:99], 2, s[20:21]
	s_waitcnt lgkmcnt(0)
	v_add_f32_e32 v82, v82, v83
	global_atomic_add_f32 v[84:85], v82, off
.LBB0_1648:
	s_or_b64 exec, exec, s[48:49]
	v_pk_add_f32 v[78:79], v[78:79], v[142:143]
	v_pk_add_f32 v[80:81], v[80:81], v[144:145]
	v_pk_add_f32 v[88:89], v[74:75], v[138:139]
	v_cvt_pk_bf16_f32 v74, v78, v79
	v_mul_f32_e32 v79, v79, v79
	v_fmac_f32_e32 v79, v78, v78
	v_mul_f32_e32 v78, v81, v81
	v_fmac_f32_e32 v78, v80, v80
	v_add_f32_e32 v78, v79, v78
	v_mul_f32_e32 v79, v89, v89
	v_pk_add_f32 v[72:73], v[72:73], v[136:137]
	v_pk_add_f32 v[70:71], v[70:71], v[134:135]
	v_pk_add_f32 v[86:87], v[76:77], v[140:141]
	v_cvt_pk_bf16_f32 v75, v80, v81
	v_fmac_f32_e32 v79, v88, v88
	v_pk_add_f32 v[80:81], v[66:67], v[130:131]
	v_mul_f32_e32 v66, v71, v71
	v_mul_f32_e32 v67, v73, v73
	v_add_f32_e32 v78, v78, v79
	v_mul_f32_e32 v79, v87, v87
	v_fmac_f32_e32 v66, v70, v70
	v_fmac_f32_e32 v67, v72, v72
	v_fmac_f32_e32 v79, v86, v86
	v_add_f32_e32 v66, v66, v67
	v_mul_f32_e32 v67, v81, v81
	v_cvt_pk_bf16_f32 v76, v88, v89
	v_cvt_pk_bf16_f32 v77, v86, v87
	v_add_f32_e32 v86, v79, v78
	v_pk_add_f32 v[78:79], v[68:69], v[132:133]
	v_fmac_f32_e32 v67, v80, v80
	v_add_f32_e32 v66, v66, v67
	v_mul_f32_e32 v67, v79, v79
	v_fmac_f32_e32 v67, v78, v78
	v_add_f32_e32 v66, v67, v66
	v_add_f32_e32 v69, v86, v66
	v_mov_b32_e32 v86, v69
	s_nop 1
	v_permlane16_swap_b32_e32 v86, v69
	v_or_b32_e32 v82, 48, v198
	s_waitcnt lgkmcnt(1)
	v_mov_b32_e32 v83, v199
	v_lshlrev_b64 v[84:85], 13, v[82:83]
	v_lshl_add_u64 v[66:67], s[18:19], 0, v[84:85]
	v_lshl_add_u64 v[84:85], v[194:195], 1, v[66:67]
	s_waitcnt lgkmcnt(0)
	v_add_f32_e32 v66, v69, v86
	v_mov_b32_e32 v67, v66
	s_nop 1
	v_permlane32_swap_b32_e32 v67, v66
	global_store_dwordx4 v[84:85], v[74:77], off
	v_cvt_pk_bf16_f32 v68, v70, v71
	v_cvt_pk_bf16_f32 v69, v72, v73
	v_cvt_pk_bf16_f32 v70, v80, v81
	v_cvt_pk_bf16_f32 v71, v78, v79
	global_store_dwordx4 v[84:85], v[68:71], off offset:256
	s_and_saveexec_b64 s[48:49], s[0:1]
	s_cbranch_execz .LBB0_1650
	v_lshl_add_u64 v[68:69], v[82:83], 2, s[20:21]
	s_waitcnt lgkmcnt(0)
	v_add_f32_e32 v66, v66, v67
	global_atomic_add_f32 v[68:69], v66, off
.LBB0_1650:
	s_or_b64 exec, exec, s[48:49]
	v_add_u32_e32 v114, 0x80, v198
	v_ashrrev_i32_e32 v115, 31, v114
	s_waitcnt lgkmcnt(0)
	v_lshlrev_b64 v[66:67], 14, v[114:115]
	v_lshl_add_u64 v[68:69], v[196:197], 0, v[66:67]
	global_load_dwordx4 v[118:121], v[68:69], off nt
	global_load_dwordx4 v[122:125], v[68:69], off offset:16 nt
	global_load_dwordx4 v[126:129], v[68:69], off offset:512 nt
	global_load_dwordx4 v[130:133], v[68:69], off offset:528 nt
	v_or_b32_e32 v68, 0x40000, v66
	v_mov_b32_e32 v69, v67
	v_or_b32_e32 v70, 0x80000, v66
	v_mov_b32_e32 v71, v67
	v_or_b32_e32 v66, 0xc0000, v66
	v_lshl_add_u64 v[68:69], v[196:197], 0, v[68:69]
	v_lshl_add_u64 v[70:71], v[196:197], 0, v[70:71]
	v_lshl_add_u64 v[72:73], v[196:197], 0, v[66:67]
	global_load_dwordx4 v[106:109], v[68:69], off offset:16 nt
	global_load_dwordx4 v[110:113], v[68:69], off nt
	global_load_dwordx4 v[98:101], v[68:69], off offset:528 nt
	global_load_dwordx4 v[102:105], v[68:69], off offset:512 nt
	global_load_dwordx4 v[90:93], v[70:71], off offset:16 nt
	global_load_dwordx4 v[94:97], v[70:71], off nt
	global_load_dwordx4 v[82:85], v[70:71], off offset:528 nt
	global_load_dwordx4 v[86:89], v[70:71], off offset:512 nt
	global_load_dwordx4 v[74:77], v[72:73], off offset:16 nt
	global_load_dwordx4 v[78:81], v[72:73], off nt
	global_load_dwordx4 v[66:69], v[72:73], off offset:528 nt
	s_nop 0
	global_load_dwordx4 v[70:73], v[72:73], off offset:512 nt
	v_lshlrev_b64 v[134:135], 13, v[114:115]
	s_waitcnt vmcnt(15)
; __device__ __forceinline__ u32x4 pack8f(f32x4 a, f32x4 b) { u32x4 w; w.x = cvtpk(a[0], a[1]); w.y = cvtpk(a[2], a[3]); w.z = cvtpk(b[0], b[1]); w.w = cvtpk(b[2], b[3]); return w; }
;     __device__ __forceinline__ void operator()(const f32x4 (&acc)[2][2][4][2], const Unit& u, int wr, int wc, int fr, int fq) const {
;     ...
;             for (int m = 0; m < 4; ++m) { const size_t row = row0 + m * 16;
;                 float sq = 0.f;
; #pragma unroll
;                 for (int bj = 0; bj < 2; ++bj) { const size_t o = row * 4096 + col + bj * HALF;
;                     const f32x4 v0 = bq[m][bj][0] + acc[ai][bj][m][0], v1 = bq[m][bj][1] + acc[ai][bj][m][1];
;                     *(u32x4*)(xb + o) = pack8f(v0, v1);
;                     sq += (v0[0] * v0[0] + v0[1] * v0[1]) + (v0[2] * v0[2] + v0[3] * v0[3]) + (v1[0] * v1[0] + v1[1] * v1[1]) + (v1[2] * v1[2] + v1[3] * v1[3]); }
;                 sq += __shfl_xor(sq, 16); sq += __shfl_xor(sq, 32);
;                 if (fq == 0) atomicAdd(ss + row, sq); }
	v_pk_add_f32 v[64:65], v[64:65], v[120:121]
	v_pk_add_f32 v[62:63], v[62:63], v[118:119]
	s_waitcnt vmcnt(13)
	v_pk_add_f32 v[56:57], v[56:57], v[128:129]
	v_pk_add_f32 v[54:55], v[54:55], v[126:127]
	v_pk_add_f32 v[60:61], v[60:61], v[124:125]
	v_pk_add_f32 v[58:59], v[58:59], v[122:123]
	s_waitcnt vmcnt(12)
	v_pk_add_f32 v[120:121], v[50:51], v[130:131]
	v_cvt_pk_bf16_f32 v50, v62, v63
	v_cvt_pk_bf16_f32 v51, v64, v65
	v_mul_f32_e32 v63, v63, v63
	v_mul_f32_e32 v65, v65, v65
	v_mul_f32_e32 v117, v55, v55
	v_mul_f32_e32 v122, v57, v57
	v_pk_add_f32 v[118:119], v[52:53], v[132:133]
	v_cvt_pk_bf16_f32 v52, v58, v59
	v_cvt_pk_bf16_f32 v53, v60, v61
	v_mul_f32_e32 v59, v59, v59
	v_mul_f32_e32 v61, v61, v61
	v_mul_f32_e32 v123, v121, v121
	v_fmac_f32_e32 v63, v62, v62
	v_fmac_f32_e32 v65, v64, v64
	v_fmac_f32_e32 v117, v54, v54
	v_fmac_f32_e32 v122, v56, v56
	v_mul_f32_e32 v124, v119, v119
	v_fmac_f32_e32 v59, v58, v58
	v_fmac_f32_e32 v61, v60, v60
	v_fmac_f32_e32 v123, v120, v120
	v_add_f32_e32 v58, v63, v65
	v_add_f32_e32 v60, v117, v122
	v_fmac_f32_e32 v124, v118, v118
	v_add_f32_e32 v58, v58, v59
	v_add_f32_e32 v59, v60, v123
	v_add_f32_e32 v58, v61, v58
	v_add_f32_e32 v59, v124, v59
	v_add_f32_e32 v60, v58, v59
	v_mov_b32_e32 v61, v60
	s_nop 1
	v_permlane16_swap_b32_e32 v61, v60
	v_lshl_add_u64 v[58:59], s[18:19], 0, v[134:135]
	v_lshl_add_u64 v[58:59], v[194:195], 1, v[58:59]
	global_store_dwordx4 v[58:59], v[50:53], off
	s_waitcnt lgkmcnt(0)
	s_nop 0
	v_add_f32_e32 v50, v60, v61
	v_mov_b32_e32 v51, v50
	s_nop 1
	v_permlane32_swap_b32_e32 v51, v50
	v_cvt_pk_bf16_f32 v52, v54, v55
	v_cvt_pk_bf16_f32 v53, v56, v57
	v_cvt_pk_bf16_f32 v54, v120, v121
	v_cvt_pk_bf16_f32 v55, v118, v119
	global_store_dwordx4 v[58:59], v[52:55], off offset:256
	s_and_saveexec_b64 s[48:49], s[0:1]
	s_cbranch_execz .LBB0_1652
	v_lshl_add_u64 v[52:53], v[114:115], 2, s[20:21]
	s_waitcnt lgkmcnt(0)
	v_add_f32_e32 v50, v50, v51
	global_atomic_add_f32 v[52:53], v50, off
.LBB0_1652:
	s_or_b64 exec, exec, s[48:49]
	s_waitcnt vmcnt(12)
	v_pk_add_f32 v[46:47], v[46:47], v[110:111]
	v_pk_add_f32 v[48:49], v[48:49], v[112:113]
	v_pk_add_f32 v[56:57], v[42:43], v[106:107]
	v_cvt_pk_bf16_f32 v42, v46, v47
	v_mul_f32_e32 v47, v47, v47
	v_fmac_f32_e32 v47, v46, v46
	v_mul_f32_e32 v46, v49, v49
	v_fmac_f32_e32 v46, v48, v48
	v_add_f32_e32 v46, v47, v46
	v_mul_f32_e32 v47, v57, v57
	s_waitcnt vmcnt(10)
	v_pk_add_f32 v[40:41], v[40:41], v[104:105]
	v_pk_add_f32 v[38:39], v[38:39], v[102:103]
	v_pk_add_f32 v[54:55], v[44:45], v[108:109]
	v_cvt_pk_bf16_f32 v43, v48, v49
	v_fmac_f32_e32 v47, v56, v56
	v_pk_add_f32 v[48:49], v[34:35], v[98:99]
	v_mul_f32_e32 v34, v39, v39
	v_mul_f32_e32 v35, v41, v41
	v_add_f32_e32 v46, v46, v47
	v_mul_f32_e32 v47, v55, v55
	v_fmac_f32_e32 v34, v38, v38
	v_fmac_f32_e32 v35, v40, v40
	v_fmac_f32_e32 v47, v54, v54
	v_add_f32_e32 v34, v34, v35
	v_mul_f32_e32 v35, v49, v49
	v_cvt_pk_bf16_f32 v44, v56, v57
	v_cvt_pk_bf16_f32 v45, v54, v55
	v_add_f32_e32 v54, v47, v46
	v_pk_add_f32 v[46:47], v[36:37], v[100:101]
	v_fmac_f32_e32 v35, v48, v48
	v_add_f32_e32 v34, v34, v35
	v_mul_f32_e32 v35, v47, v47
	v_fmac_f32_e32 v35, v46, v46
	v_add_f32_e32 v34, v35, v34
	v_add_f32_e32 v37, v54, v34
	v_mov_b32_e32 v54, v37
	s_nop 1
	v_permlane16_swap_b32_e32 v54, v37
	v_or_b32_e32 v50, 16, v114
	s_waitcnt lgkmcnt(1)
	v_mov_b32_e32 v51, v115
	v_lshlrev_b64 v[52:53], 13, v[50:51]
	v_lshl_add_u64 v[34:35], s[18:19], 0, v[52:53]
	v_lshl_add_u64 v[52:53], v[194:195], 1, v[34:35]
	s_waitcnt lgkmcnt(0)
	v_add_f32_e32 v34, v37, v54
	v_mov_b32_e32 v35, v34
	s_nop 1
	v_permlane32_swap_b32_e32 v35, v34
	global_store_dwordx4 v[52:53], v[42:45], off
	v_cvt_pk_bf16_f32 v36, v38, v39
	v_cvt_pk_bf16_f32 v37, v40, v41
	v_cvt_pk_bf16_f32 v38, v48, v49
	v_cvt_pk_bf16_f32 v39, v46, v47
	global_store_dwordx4 v[52:53], v[36:39], off offset:256
	s_and_saveexec_b64 s[48:49], s[0:1]
	s_cbranch_execz .LBB0_1654
	v_lshl_add_u64 v[36:37], v[50:51], 2, s[20:21]
	s_waitcnt lgkmcnt(0)
	v_add_f32_e32 v34, v34, v35
	global_atomic_add_f32 v[36:37], v34, off
; __device__ __forceinline__ u32x4 pack8f(f32x4 a, f32x4 b) { u32x4 w; w.x = cvtpk(a[0], a[1]); w.y = cvtpk(a[2], a[3]); w.z = cvtpk(b[0], b[1]); w.w = cvtpk(b[2], b[3]); return w; }
;     __device__ __forceinline__ void operator()(const f32x4 (&acc)[2][2][4][2], const Unit& u, int wr, int wc, int fr, int fq) const {
;     ...
;             for (int m = 0; m < 4; ++m) { const size_t row = row0 + m * 16;
;                 float sq = 0.f;
; #pragma unroll
;                 for (int bj = 0; bj < 2; ++bj) { const size_t o = row * 4096 + col + bj * HALF;
;                     const f32x4 v0 = bq[m][bj][0] + acc[ai][bj][m][0], v1 = bq[m][bj][1] + acc[ai][bj][m][1];
;                     *(u32x4*)(xb + o) = pack8f(v0, v1);
;                     sq += (v0[0] * v0[0] + v0[1] * v0[1]) + (v0[2] * v0[2] + v0[3] * v0[3]) + (v1[0] * v1[0] + v1[1] * v1[1]) + (v1[2] * v1[2] + v1[3] * v1[3]); }
;                 sq += __shfl_xor(sq, 16); sq += __shfl_xor(sq, 32);
;                 if (fq == 0) atomicAdd(ss + row, sq); }
.LBB0_1654:
	s_or_b64 exec, exec, s[48:49]
	s_waitcnt vmcnt(10)
	v_pk_add_f32 v[30:31], v[30:31], v[94:95]
	v_pk_add_f32 v[32:33], v[32:33], v[96:97]
	v_pk_add_f32 v[40:41], v[26:27], v[90:91]
	v_cvt_pk_bf16_f32 v26, v30, v31
	v_mul_f32_e32 v31, v31, v31
	v_fmac_f32_e32 v31, v30, v30
	v_mul_f32_e32 v30, v33, v33
	v_fmac_f32_e32 v30, v32, v32
	v_add_f32_e32 v30, v31, v30
	v_mul_f32_e32 v31, v41, v41
	s_waitcnt vmcnt(8)
	v_pk_add_f32 v[24:25], v[24:25], v[88:89]
	v_pk_add_f32 v[22:23], v[22:23], v[86:87]
	v_pk_add_f32 v[38:39], v[28:29], v[92:93]
	v_cvt_pk_bf16_f32 v27, v32, v33
	v_fmac_f32_e32 v31, v40, v40
	v_pk_add_f32 v[32:33], v[18:19], v[82:83]
	v_mul_f32_e32 v18, v23, v23
	v_mul_f32_e32 v19, v25, v25
	v_add_f32_e32 v30, v30, v31
	v_mul_f32_e32 v31, v39, v39
	v_fmac_f32_e32 v18, v22, v22
	v_fmac_f32_e32 v19, v24, v24
	v_fmac_f32_e32 v31, v38, v38
	v_add_f32_e32 v18, v18, v19
	v_mul_f32_e32 v19, v33, v33
	v_cvt_pk_bf16_f32 v28, v40, v41
	v_cvt_pk_bf16_f32 v29, v38, v39
	v_add_f32_e32 v38, v31, v30
	v_pk_add_f32 v[30:31], v[20:21], v[84:85]
	v_fmac_f32_e32 v19, v32, v32
	v_add_f32_e32 v18, v18, v19
	v_mul_f32_e32 v19, v31, v31
	v_fmac_f32_e32 v19, v30, v30
	v_add_f32_e32 v18, v19, v18
	v_add_f32_e32 v21, v38, v18
	v_mov_b32_e32 v38, v21
	s_nop 1
	v_permlane16_swap_b32_e32 v38, v21
	v_or_b32_e32 v34, 32, v114
	s_waitcnt lgkmcnt(1)
	v_mov_b32_e32 v35, v115
	v_lshlrev_b64 v[36:37], 13, v[34:35]
	v_lshl_add_u64 v[18:19], s[18:19], 0, v[36:37]
	v_lshl_add_u64 v[36:37], v[194:195], 1, v[18:19]
	s_waitcnt lgkmcnt(0)
	v_add_f32_e32 v18, v21, v38
	v_mov_b32_e32 v19, v18
	s_nop 1
	v_permlane32_swap_b32_e32 v19, v18
	global_store_dwordx4 v[36:37], v[26:29], off
	v_cvt_pk_bf16_f32 v20, v22, v23
	v_cvt_pk_bf16_f32 v21, v24, v25
	v_cvt_pk_bf16_f32 v22, v32, v33
	v_cvt_pk_bf16_f32 v23, v30, v31
	global_store_dwordx4 v[36:37], v[20:23], off offset:256
	s_and_saveexec_b64 s[48:49], s[0:1]
	s_cbranch_execz .LBB0_1656
	v_lshl_add_u64 v[20:21], v[34:35], 2, s[20:21]
	s_waitcnt lgkmcnt(0)
	v_add_f32_e32 v18, v18, v19
	global_atomic_add_f32 v[20:21], v18, off
.LBB0_1656:
	s_or_b64 exec, exec, s[48:49]
	s_waitcnt vmcnt(8)
	v_pk_add_f32 v[14:15], v[14:15], v[78:79]
	v_pk_add_f32 v[16:17], v[16:17], v[80:81]
	v_pk_add_f32 v[22:23], v[10:11], v[74:75]
	v_cvt_pk_bf16_f32 v10, v14, v15
	v_mul_f32_e32 v15, v15, v15
	v_fmac_f32_e32 v15, v14, v14
	v_mul_f32_e32 v14, v17, v17
	v_fmac_f32_e32 v14, v16, v16
	v_add_f32_e32 v14, v15, v14
	v_mul_f32_e32 v15, v23, v23
	s_waitcnt vmcnt(6)
	v_pk_add_f32 v[8:9], v[8:9], v[72:73]
	v_pk_add_f32 v[6:7], v[6:7], v[70:71]
	v_pk_add_f32 v[20:21], v[12:13], v[76:77]
	v_cvt_pk_bf16_f32 v11, v16, v17
	v_fmac_f32_e32 v15, v22, v22
	v_pk_add_f32 v[16:17], v[2:3], v[66:67]
	v_mul_f32_e32 v2, v7, v7
	v_mul_f32_e32 v3, v9, v9
	v_add_f32_e32 v14, v14, v15
	v_mul_f32_e32 v15, v21, v21
	v_fmac_f32_e32 v2, v6, v6
	v_fmac_f32_e32 v3, v8, v8
	v_fmac_f32_e32 v15, v20, v20
	v_add_f32_e32 v2, v2, v3
	v_mul_f32_e32 v3, v17, v17
	v_cvt_pk_bf16_f32 v12, v22, v23
	v_cvt_pk_bf16_f32 v13, v20, v21
	v_add_f32_e32 v20, v15, v14
	v_pk_add_f32 v[14:15], v[4:5], v[68:69]
	v_fmac_f32_e32 v3, v16, v16
	v_add_f32_e32 v2, v2, v3
	v_mul_f32_e32 v3, v15, v15
	v_fmac_f32_e32 v3, v14, v14
	v_add_f32_e32 v2, v3, v2
	v_add_f32_e32 v5, v20, v2
	v_mov_b32_e32 v20, v5
	s_nop 1
	v_permlane16_swap_b32_e32 v20, v5
	v_or_b32_e32 v114, 48, v114
	s_waitcnt lgkmcnt(1)
	v_lshlrev_b64 v[18:19], 13, v[114:115]
	v_lshl_add_u64 v[2:3], s[18:19], 0, v[18:19]
	v_lshl_add_u64 v[18:19], v[194:195], 1, v[2:3]
	s_waitcnt lgkmcnt(0)
	v_add_f32_e32 v2, v5, v20
	v_mov_b32_e32 v3, v2
	s_nop 1
	v_permlane32_swap_b32_e32 v3, v2
	global_store_dwordx4 v[18:19], v[10:13], off
	v_cvt_pk_bf16_f32 v4, v6, v7
	v_cvt_pk_bf16_f32 v5, v8, v9
	v_cvt_pk_bf16_f32 v6, v16, v17
	v_cvt_pk_bf16_f32 v7, v14, v15
	global_store_dwordx4 v[18:19], v[4:7], off offset:256
	s_and_saveexec_b64 s[48:49], s[0:1]
	s_cbranch_execz .LBB0_1658
	v_lshl_add_u64 v[4:5], v[114:115], 2, s[20:21]
	s_waitcnt lgkmcnt(0)
	v_add_f32_e32 v2, v2, v3
	global_atomic_add_f32 v[4:5], v2, off

; __device__ __forceinline__ u32x4 pack8f(f32x4 a, f32x4 b) { u32x4 w; w.x = cvtpk(a[0], a[1]); w.y = cvtpk(a[2], a[3]); w.z = cvtpk(b[0], b[1]); w.w = cvtpk(b[2], b[3]); return w; }
; __device__ __forceinline__ void unpack8f(u32x4 w, f32x4& a, f32x4& b) { a = (f32x4){bflo(w.x), bfhi(w.x), bflo(w.y), bfhi(w.y)}; b = (f32x4){bflo(w.z), bfhi(w.z), bflo(w.w), bfhi(w.w)}; }
;     __device__ __forceinline__ void operator()(const f32x4 (&acc)[2][2][4][2], const Unit& u, int wr, int wc, int fr, int fq) const {
;     ...
;                 u32x4 raw[4][2];
; #pragma unroll
;                 for (int m = 0; m < 4; ++m)
; #pragma unroll
;                     for (int bj = 0; bj < 2; ++bj) raw[m][bj] = __builtin_nontemporal_load((const u32x4*)((const bf16_t*)base + (row0 + m * 16) * 4096 + col + bj * HALF));
;                 asm volatile("" ::: "memory");
; #pragma unroll
;                 for (int m = 0; m < 4; ++m)
; #pragma unroll
;                     for (int bj = 0; bj < 2; ++bj) unpack8f(raw[m][bj], bq[m][bj][0], bq[m][bj][1]);
;             } else {
; #pragma unroll
;                 for (int m = 0; m < 4; ++m)
; #pragma unroll
;                     for (int bj = 0; bj < 2; ++bj) { const float* p = (const float*)base + (row0 + m * 16) * 4096 + col + bj * HALF; bq[m][bj][0] = __builtin_nontemporal_load((const f32x4*)p); bq[m][bj][1] = __builtin_nontemporal_load((const f32x4*)(p + 4)); }
;                 asm volatile("" ::: "memory");
;             }
; #pragma unroll
;             for (int m = 0; m < 4; ++m) { const size_t row = row0 + m * 16;
;                 float sq = 0.f;
; #pragma unroll
;                 for (int bj = 0; bj < 2; ++bj) { const size_t o = row * 4096 + col + bj * HALF;
;                     const f32x4 v0 = bq[m][bj][0] + acc[ai][bj][m][0], v1 = bq[m][bj][1] + acc[ai][bj][m][1];
;                     *(u32x4*)(xb + o) = pack8f(v0, v1);
;                     sq += (v0[0] * v0[0] + v0[1] * v0[1]) + (v0[2] * v0[2] + v0[3] * v0[3]) + (v1[0] * v1[0] + v1[1] * v1[1]) + (v1[2] * v1[2] + v1[3] * v1[3]); }
;                 sq += __shfl_xor(sq, 16); sq += __shfl_xor(sq, 32);
;                 if (fq == 0) atomicAdd(ss + row, sq); }
.LBB0_2063:
	v_lshl_or_b32 v170, s50, 8, v186
	v_lshl_add_u32 v174, s49, 8, v184
	v_ashrrev_i32_e32 v171, 31, v170
	v_ashrrev_i32_e32 v175, 31, v174
	v_lshlrev_b64 v[200:201], 1, v[170:171]
	v_lshl_add_u64 v[172:173], s[14:15], 0, v[200:201]
	v_lshlrev_b64 v[202:203], 13, v[174:175]
	v_lshl_add_u64 v[130:131], v[172:173], 0, v[202:203]
	global_load_dwordx4 v[192:195], v[130:131], off nt
	global_load_dwordx4 v[196:199], v[130:131], off offset:256 nt
	v_add_co_u32_e32 v132, vcc, 0x20000, v130
	v_and_b32_e32 v204, 64, v190
	s_nop 0
	v_addc_co_u32_e32 v133, vcc, 0, v131, vcc
	v_add_co_u32_e32 v134, vcc, 0x40000, v130
	global_load_dwordx4 v[150:153], v[132:133], off nt
	global_load_dwordx4 v[146:149], v[132:133], off offset:256 nt
	v_addc_co_u32_e32 v135, vcc, 0, v131, vcc
	v_add_co_u32_e32 v130, vcc, 0x60000, v130
	global_load_dwordx4 v[142:145], v[134:135], off nt
	global_load_dwordx4 v[138:141], v[134:135], off offset:256 nt
	v_addc_co_u32_e32 v131, vcc, 0, v131, vcc
	global_load_dwordx4 v[134:137], v[130:131], off nt
	s_nop 0
	global_load_dwordx4 v[130:133], v[130:131], off offset:256 nt
	v_xor_b32_e32 v191, 16, v190
	v_add_u32_e32 v204, 64, v204
	v_xor_b32_e32 v205, 32, v190
	v_cmp_lt_i32_e32 vcc, v191, v204
	v_lshl_add_u64 v[202:203], s[14:15], 0, v[202:203]
	v_lshl_add_u64 v[200:201], v[202:203], 0, v[200:201]
	v_cndmask_b32_e32 v191, v190, v191, vcc
	v_cmp_lt_i32_e32 vcc, v205, v204
	v_lshlrev_b32_e32 v191, 2, v191
	s_waitcnt vmcnt(0)
	v_lshlrev_b32_e32 v202, 16, v192
	v_and_b32_e32 v203, 0xffff0000, v192
	v_lshlrev_b32_e32 v192, 16, v193
	v_and_b32_e32 v193, 0xffff0000, v193
	v_lshlrev_b32_e32 v206, 16, v196
	v_and_b32_e32 v207, 0xffff0000, v196
	v_lshlrev_b32_e32 v196, 16, v197
	v_and_b32_e32 v197, 0xffff0000, v197
	v_cndmask_b32_e32 v210, v190, v205, vcc
	v_lshlrev_b32_e32 v204, 16, v194
	v_and_b32_e32 v205, 0xffff0000, v194
	v_lshlrev_b32_e32 v194, 16, v195
	v_and_b32_e32 v195, 0xffff0000, v195
	v_lshlrev_b32_e32 v208, 16, v198
	v_and_b32_e32 v209, 0xffff0000, v198
	v_lshlrev_b32_e32 v198, 16, v199
	v_and_b32_e32 v199, 0xffff0000, v199
	v_pk_add_f32 v[128:129], v[128:129], v[192:193]
	v_pk_add_f32 v[126:127], v[126:127], v[202:203]
	v_pk_add_f32 v[120:121], v[120:121], v[196:197]
	v_pk_add_f32 v[118:119], v[118:119], v[206:207]
	v_pk_add_f32 v[124:125], v[124:125], v[194:195]
	v_pk_add_f32 v[122:123], v[122:123], v[204:205]
	v_pk_add_f32 v[192:193], v[116:117], v[198:199]
	v_pk_add_f32 v[194:195], v[114:115], v[208:209]
	v_mul_f32_e32 v116, v127, v127
	v_mul_f32_e32 v117, v129, v129
	v_mul_f32_e32 v196, v119, v119
	v_mul_f32_e32 v197, v121, v121
	v_cvt_pk_bf16_f32 v114, v126, v127
	v_mul_f32_e32 v127, v123, v123
	v_mul_f32_e32 v198, v195, v195
	v_fmac_f32_e32 v116, v126, v126
	v_fmac_f32_e32 v117, v128, v128
	v_fmac_f32_e32 v196, v118, v118
	v_fmac_f32_e32 v197, v120, v120
	v_cvt_pk_bf16_f32 v115, v128, v129
	v_mul_f32_e32 v129, v125, v125
	v_mul_f32_e32 v199, v193, v193
	v_fmac_f32_e32 v127, v122, v122
	v_fmac_f32_e32 v198, v194, v194
	v_add_f32_e32 v116, v116, v117
	v_add_f32_e32 v117, v196, v197
	v_fmac_f32_e32 v129, v124, v124
	v_fmac_f32_e32 v199, v192, v192
	v_add_f32_e32 v116, v127, v116
	v_add_f32_e32 v117, v198, v117
	v_add_f32_e32 v116, v129, v116
	v_add_f32_e32 v117, v199, v117
	v_add_f32_e32 v126, v116, v117
	v_mov_b32_e32 v127, v126
	s_nop 1
	v_permlane16_swap_b32_e32 v127, v126
	v_cvt_pk_bf16_f32 v116, v122, v123
	v_cvt_pk_bf16_f32 v117, v124, v125
	global_store_dwordx4 v[200:201], v[114:117], off
	v_cvt_pk_bf16_f32 v118, v118, v119
	v_cvt_pk_bf16_f32 v119, v120, v121
	v_cvt_pk_bf16_f32 v120, v194, v195
	v_cvt_pk_bf16_f32 v121, v192, v193
	global_store_dwordx4 v[200:201], v[118:121], off offset:256
	s_waitcnt lgkmcnt(0)
	v_add_f32_e32 v114, v126, v127
	v_lshlrev_b32_e32 v116, 2, v210
	v_mov_b32_e32 v115, v114
	s_nop 1
	v_permlane32_swap_b32_e32 v115, v114
	s_and_saveexec_b64 s[24:25], s[2:3]
	s_cbranch_execz .LBB0_2065
	v_lshl_add_u64 v[118:119], v[174:175], 2, s[16:17]
	s_waitcnt lgkmcnt(0)
	v_add_f32_e32 v114, v114, v115
	global_atomic_add_f32 v[118:119], v114, off
.LBB0_2065:
	s_or_b64 exec, exec, s[24:25]
	v_lshlrev_b32_e32 v118, 16, v150
	v_and_b32_e32 v119, 0xffff0000, v150
	v_lshlrev_b32_e32 v120, 16, v151
	v_and_b32_e32 v121, 0xffff0000, v151
	v_lshlrev_b32_e32 v122, 16, v152
	v_and_b32_e32 v123, 0xffff0000, v152
	v_pk_add_f32 v[110:111], v[110:111], v[118:119]
	v_pk_add_f32 v[112:113], v[112:113], v[120:121]
	v_pk_add_f32 v[120:121], v[106:107], v[122:123]
	v_cvt_pk_bf16_f32 v106, v110, v111
	v_mul_f32_e32 v111, v111, v111
	v_fmac_f32_e32 v111, v110, v110
	v_mul_f32_e32 v110, v113, v113
	v_lshlrev_b32_e32 v126, 16, v146
	v_and_b32_e32 v127, 0xffff0000, v146
	v_lshlrev_b32_e32 v128, 16, v147
	v_and_b32_e32 v129, 0xffff0000, v147
	v_fmac_f32_e32 v110, v112, v112
	v_lshlrev_b32_e32 v124, 16, v153
	v_and_b32_e32 v125, 0xffff0000, v153
	v_lshlrev_b32_e32 v146, 16, v148
	v_and_b32_e32 v147, 0xffff0000, v148
	v_add_f32_e32 v110, v111, v110
	v_mul_f32_e32 v111, v121, v121
	v_pk_add_f32 v[104:105], v[104:105], v[128:129]
	v_pk_add_f32 v[102:103], v[102:103], v[126:127]
	v_pk_add_f32 v[118:119], v[108:109], v[124:125]
	v_cvt_pk_bf16_f32 v107, v112, v113
	v_fmac_f32_e32 v111, v120, v120
	v_pk_add_f32 v[112:113], v[98:99], v[146:147]
	v_mul_f32_e32 v98, v103, v103
	v_mul_f32_e32 v99, v105, v105
	v_add_f32_e32 v110, v111, v110
	v_mul_f32_e32 v111, v119, v119
	v_fmac_f32_e32 v98, v102, v102
	v_fmac_f32_e32 v99, v104, v104
	v_lshlrev_b32_e32 v148, 16, v149
	v_and_b32_e32 v149, 0xffff0000, v149
	v_fmac_f32_e32 v111, v118, v118
	v_add_f32_e32 v98, v98, v99
	v_mul_f32_e32 v99, v113, v113
	v_add_f32_e32 v117, v111, v110
	v_pk_add_f32 v[110:111], v[100:101], v[148:149]
	v_fmac_f32_e32 v99, v112, v112
	v_add_f32_e32 v98, v99, v98
	v_mul_f32_e32 v99, v111, v111
	v_fmac_f32_e32 v99, v110, v110
	v_add_f32_e32 v98, v99, v98
	v_add_f32_e32 v101, v117, v98
	v_mov_b32_e32 v117, v101
	s_nop 1
	v_permlane16_swap_b32_e32 v117, v101
	v_or_b32_e32 v114, 16, v174
	s_waitcnt lgkmcnt(1)
	v_mov_b32_e32 v115, v175
	v_lshlrev_b64 v[150:151], 13, v[114:115]
	v_lshl_add_u64 v[98:99], s[14:15], 0, v[150:151]
	v_cvt_pk_bf16_f32 v108, v120, v121
	v_cvt_pk_bf16_f32 v109, v118, v119
	v_lshl_add_u64 v[118:119], v[170:171], 1, v[98:99]
	s_waitcnt lgkmcnt(0)
	v_add_f32_e32 v98, v101, v117
	v_mov_b32_e32 v99, v98
	s_nop 1
	v_permlane32_swap_b32_e32 v99, v98
	global_store_dwordx4 v[118:119], v[106:109], off
	v_cvt_pk_bf16_f32 v100, v102, v103
	v_cvt_pk_bf16_f32 v101, v104, v105
	v_cvt_pk_bf16_f32 v102, v112, v113
	v_cvt_pk_bf16_f32 v103, v110, v111
	global_store_dwordx4 v[118:119], v[100:103], off offset:256
	s_and_saveexec_b64 s[24:25], s[2:3]
	s_cbranch_execz .LBB0_2067
	v_lshl_add_u64 v[100:101], v[114:115], 2, s[16:17]
	s_waitcnt lgkmcnt(0)
	v_add_f32_e32 v98, v98, v99
	global_atomic_add_f32 v[100:101], v98, off
; __device__ __forceinline__ u32x4 pack8f(f32x4 a, f32x4 b) { u32x4 w; w.x = cvtpk(a[0], a[1]); w.y = cvtpk(a[2], a[3]); w.z = cvtpk(b[0], b[1]); w.w = cvtpk(b[2], b[3]); return w; }
;     __device__ __forceinline__ void operator()(const f32x4 (&acc)[2][2][4][2], const Unit& u, int wr, int wc, int fr, int fq) const {
;     ...
;             for (int m = 0; m < 4; ++m) { const size_t row = row0 + m * 16;
;                 float sq = 0.f;
; #pragma unroll
;                 for (int bj = 0; bj < 2; ++bj) { const size_t o = row * 4096 + col + bj * HALF;
;                     const f32x4 v0 = bq[m][bj][0] + acc[ai][bj][m][0], v1 = bq[m][bj][1] + acc[ai][bj][m][1];
;                     *(u32x4*)(xb + o) = pack8f(v0, v1);
;                     sq += (v0[0] * v0[0] + v0[1] * v0[1]) + (v0[2] * v0[2] + v0[3] * v0[3]) + (v1[0] * v1[0] + v1[1] * v1[1]) + (v1[2] * v1[2] + v1[3] * v1[3]); }
;                 sq += __shfl_xor(sq, 16); sq += __shfl_xor(sq, 32);
;                 if (fq == 0) atomicAdd(ss + row, sq); }
.LBB0_2067:
	s_or_b64 exec, exec, s[24:25]
	v_lshlrev_b32_e32 v100, 16, v142
	v_and_b32_e32 v101, 0xffff0000, v142
	v_lshlrev_b32_e32 v102, 16, v143
	v_and_b32_e32 v103, 0xffff0000, v143
	v_lshlrev_b32_e32 v104, 16, v144
	v_and_b32_e32 v105, 0xffff0000, v144
	v_pk_add_f32 v[94:95], v[94:95], v[100:101]
	v_pk_add_f32 v[96:97], v[96:97], v[102:103]
	v_pk_add_f32 v[102:103], v[90:91], v[104:105]
	v_cvt_pk_bf16_f32 v90, v94, v95
	v_mul_f32_e32 v95, v95, v95
	v_fmac_f32_e32 v95, v94, v94
	v_mul_f32_e32 v94, v97, v97
	v_lshlrev_b32_e32 v108, 16, v138
	v_and_b32_e32 v109, 0xffff0000, v138
	v_lshlrev_b32_e32 v110, 16, v139
	v_and_b32_e32 v111, 0xffff0000, v139
	v_fmac_f32_e32 v94, v96, v96
	v_lshlrev_b32_e32 v106, 16, v145
	v_and_b32_e32 v107, 0xffff0000, v145
	v_lshlrev_b32_e32 v112, 16, v140
	v_and_b32_e32 v113, 0xffff0000, v140
	v_add_f32_e32 v94, v95, v94
	v_mul_f32_e32 v95, v103, v103
	v_pk_add_f32 v[88:89], v[88:89], v[110:111]
	v_pk_add_f32 v[86:87], v[86:87], v[108:109]
	v_pk_add_f32 v[100:101], v[92:93], v[106:107]
	v_cvt_pk_bf16_f32 v91, v96, v97
	v_fmac_f32_e32 v95, v102, v102
	v_pk_add_f32 v[96:97], v[82:83], v[112:113]
	v_mul_f32_e32 v82, v87, v87
	v_mul_f32_e32 v83, v89, v89
	v_add_f32_e32 v94, v95, v94
	v_mul_f32_e32 v95, v101, v101
	v_fmac_f32_e32 v82, v86, v86
	v_fmac_f32_e32 v83, v88, v88
	v_lshlrev_b32_e32 v114, 16, v141
	v_and_b32_e32 v115, 0xffff0000, v141
	v_fmac_f32_e32 v95, v100, v100
	v_add_f32_e32 v82, v82, v83
	v_mul_f32_e32 v83, v97, v97
	v_cvt_pk_bf16_f32 v92, v102, v103
	v_cvt_pk_bf16_f32 v93, v100, v101
	v_add_f32_e32 v100, v95, v94
	v_pk_add_f32 v[94:95], v[84:85], v[114:115]
	v_fmac_f32_e32 v83, v96, v96
	v_add_f32_e32 v82, v83, v82
	v_mul_f32_e32 v83, v95, v95
	v_fmac_f32_e32 v83, v94, v94
	v_add_f32_e32 v82, v83, v82
	v_add_f32_e32 v85, v100, v82
	v_mov_b32_e32 v102, v85
	s_nop 1
	v_permlane16_swap_b32_e32 v102, v85
	v_or_b32_e32 v98, 32, v174
	s_waitcnt lgkmcnt(1)
	v_mov_b32_e32 v99, v175
	v_lshlrev_b64 v[118:119], 13, v[98:99]
	v_lshl_add_u64 v[82:83], s[14:15], 0, v[118:119]
	v_lshl_add_u64 v[100:101], v[170:171], 1, v[82:83]
	s_waitcnt lgkmcnt(0)
	v_add_f32_e32 v82, v85, v102
	v_mov_b32_e32 v83, v82
	s_nop 1
	v_permlane32_swap_b32_e32 v83, v82
	global_store_dwordx4 v[100:101], v[90:93], off
	v_cvt_pk_bf16_f32 v84, v86, v87
	v_cvt_pk_bf16_f32 v85, v88, v89
	v_cvt_pk_bf16_f32 v86, v96, v97
	v_cvt_pk_bf16_f32 v87, v94, v95
	global_store_dwordx4 v[100:101], v[84:87], off offset:256
	s_and_saveexec_b64 s[24:25], s[2:3]
	v_readlane_b32 s56, v254, 13
	v_readlane_b32 s57, v254, 14
	s_cbranch_execz .LBB0_2069
	v_lshl_add_u64 v[84:85], v[98:99], 2, s[16:17]
	s_waitcnt lgkmcnt(0)
	v_add_f32_e32 v82, v82, v83
	global_atomic_add_f32 v[84:85], v82, off
.LBB0_2069:
	s_or_b64 exec, exec, s[24:25]
	v_lshlrev_b32_e32 v84, 16, v134
	v_and_b32_e32 v85, 0xffff0000, v134
	v_lshlrev_b32_e32 v86, 16, v135
	v_and_b32_e32 v87, 0xffff0000, v135
	v_lshlrev_b32_e32 v88, 16, v136
	v_and_b32_e32 v89, 0xffff0000, v136
	v_pk_add_f32 v[78:79], v[78:79], v[84:85]
	v_pk_add_f32 v[80:81], v[80:81], v[86:87]
	v_pk_add_f32 v[86:87], v[74:75], v[88:89]
	v_cvt_pk_bf16_f32 v74, v78, v79
	v_mul_f32_e32 v79, v79, v79
	v_fmac_f32_e32 v79, v78, v78
	v_mul_f32_e32 v78, v81, v81
	v_lshlrev_b32_e32 v92, 16, v130
	v_and_b32_e32 v93, 0xffff0000, v130
	v_lshlrev_b32_e32 v94, 16, v131
	v_and_b32_e32 v95, 0xffff0000, v131
	v_fmac_f32_e32 v78, v80, v80
	v_lshlrev_b32_e32 v90, 16, v137
	v_and_b32_e32 v91, 0xffff0000, v137
	v_lshlrev_b32_e32 v96, 16, v132
	v_and_b32_e32 v97, 0xffff0000, v132
	v_add_f32_e32 v78, v79, v78
	v_mul_f32_e32 v79, v87, v87
	v_pk_add_f32 v[72:73], v[72:73], v[94:95]
	v_pk_add_f32 v[70:71], v[70:71], v[92:93]
	v_pk_add_f32 v[84:85], v[76:77], v[90:91]
	v_cvt_pk_bf16_f32 v75, v80, v81
	v_fmac_f32_e32 v79, v86, v86
	v_pk_add_f32 v[80:81], v[66:67], v[96:97]
	v_mul_f32_e32 v66, v71, v71
	v_mul_f32_e32 v67, v73, v73
	v_add_f32_e32 v78, v79, v78
	v_mul_f32_e32 v79, v85, v85
	v_fmac_f32_e32 v66, v70, v70
	v_fmac_f32_e32 v67, v72, v72
	v_lshlrev_b32_e32 v98, 16, v133
	v_and_b32_e32 v99, 0xffff0000, v133
	v_fmac_f32_e32 v79, v84, v84
	v_add_f32_e32 v66, v66, v67
	v_mul_f32_e32 v67, v81, v81
	v_cvt_pk_bf16_f32 v76, v86, v87
	v_cvt_pk_bf16_f32 v77, v84, v85
	v_add_f32_e32 v84, v79, v78
	v_pk_add_f32 v[78:79], v[68:69], v[98:99]
	v_fmac_f32_e32 v67, v80, v80
	v_add_f32_e32 v66, v67, v66
	v_mul_f32_e32 v67, v79, v79
	v_fmac_f32_e32 v67, v78, v78
	v_add_f32_e32 v66, v67, v66
	v_add_f32_e32 v69, v84, v66
	v_mov_b32_e32 v86, v69
	s_nop 1
	v_permlane16_swap_b32_e32 v86, v69
	v_or_b32_e32 v82, 48, v174
	s_waitcnt lgkmcnt(1)
	v_mov_b32_e32 v83, v175
	v_lshlrev_b64 v[100:101], 13, v[82:83]
	v_lshl_add_u64 v[66:67], s[14:15], 0, v[100:101]
	v_lshl_add_u64 v[84:85], v[170:171], 1, v[66:67]
	s_waitcnt lgkmcnt(0)
	v_add_f32_e32 v66, v69, v86
	v_mov_b32_e32 v67, v66
	s_nop 1
	v_permlane32_swap_b32_e32 v67, v66
	global_store_dwordx4 v[84:85], v[74:77], off
	v_cvt_pk_bf16_f32 v68, v70, v71
	v_cvt_pk_bf16_f32 v69, v72, v73
	v_cvt_pk_bf16_f32 v70, v80, v81
	v_cvt_pk_bf16_f32 v71, v78, v79
	global_store_dwordx4 v[84:85], v[68:71], off offset:256
	s_and_saveexec_b64 s[24:25], s[2:3]
	s_cbranch_execz .LBB0_2071
	v_lshl_add_u64 v[68:69], v[82:83], 2, s[16:17]
	s_waitcnt lgkmcnt(0)
	v_add_f32_e32 v66, v66, v67
	global_atomic_add_f32 v[68:69], v66, off
; __device__ __forceinline__ u32x4 pack8f(f32x4 a, f32x4 b) { u32x4 w; w.x = cvtpk(a[0], a[1]); w.y = cvtpk(a[2], a[3]); w.z = cvtpk(b[0], b[1]); w.w = cvtpk(b[2], b[3]); return w; }
; __device__ __forceinline__ void unpack8f(u32x4 w, f32x4& a, f32x4& b) { a = (f32x4){bflo(w.x), bfhi(w.x), bflo(w.y), bfhi(w.y)}; b = (f32x4){bflo(w.z), bfhi(w.z), bflo(w.w), bfhi(w.w)}; }
;     __device__ __forceinline__ void operator()(const f32x4 (&acc)[2][2][4][2], const Unit& u, int wr, int wc, int fr, int fq) const {
;     ...
;             if (BASE_BF16) {
;                 u32x4 raw[4][2];
; #pragma unroll
;                 for (int m = 0; m < 4; ++m)
; #pragma unroll
;                     for (int bj = 0; bj < 2; ++bj) raw[m][bj] = __builtin_nontemporal_load((const u32x4*)((const bf16_t*)base + (row0 + m * 16) * 4096 + col + bj * HALF));
;                 asm volatile("" ::: "memory");
; #pragma unroll
;                 for (int m = 0; m < 4; ++m)
; #pragma unroll
;                     for (int bj = 0; bj < 2; ++bj) unpack8f(raw[m][bj], bq[m][bj][0], bq[m][bj][1]);
;             } else {
; #pragma unroll
;                 for (int m = 0; m < 4; ++m)
; #pragma unroll
;                     for (int bj = 0; bj < 2; ++bj) { const float* p = (const float*)base + (row0 + m * 16) * 4096 + col + bj * HALF; bq[m][bj][0] = __builtin_nontemporal_load((const f32x4*)p); bq[m][bj][1] = __builtin_nontemporal_load((const f32x4*)(p + 4)); }
;                 asm volatile("" ::: "memory");
;             }
; #pragma unroll
;             for (int m = 0; m < 4; ++m) { const size_t row = row0 + m * 16;
;                 float sq = 0.f;
; #pragma unroll
;                 for (int bj = 0; bj < 2; ++bj) { const size_t o = row * 4096 + col + bj * HALF;
;                     const f32x4 v0 = bq[m][bj][0] + acc[ai][bj][m][0], v1 = bq[m][bj][1] + acc[ai][bj][m][1];
;                     *(u32x4*)(xb + o) = pack8f(v0, v1);
;                     sq += (v0[0] * v0[0] + v0[1] * v0[1]) + (v0[2] * v0[2] + v0[3] * v0[3]) + (v1[0] * v1[0] + v1[1] * v1[1]) + (v1[2] * v1[2] + v1[3] * v1[3]); }
;                 sq += __shfl_xor(sq, 16); sq += __shfl_xor(sq, 32);
;                 if (fq == 0) atomicAdd(ss + row, sq); }
.LBB0_2071:
	s_or_b64 exec, exec, s[24:25]
	v_add_u32_e32 v90, 0x80, v174
	v_ashrrev_i32_e32 v91, 31, v90
	v_lshlrev_b64 v[100:101], 13, v[90:91]
	s_waitcnt lgkmcnt(0)
	v_lshl_add_u64 v[66:67], v[172:173], 0, v[100:101]
	global_load_dwordx4 v[92:95], v[66:67], off nt
	global_load_dwordx4 v[96:99], v[66:67], off offset:256 nt
	v_or_b32_e32 v66, 0x20000, v100
	v_mov_b32_e32 v67, v101
	v_or_b32_e32 v68, 0x40000, v100
	v_mov_b32_e32 v69, v101
	v_or_b32_e32 v70, 0x60000, v100
	v_mov_b32_e32 v71, v101
	v_lshl_add_u64 v[66:67], v[172:173], 0, v[66:67]
	v_lshl_add_u64 v[68:69], v[172:173], 0, v[68:69]
	v_lshl_add_u64 v[102:103], v[172:173], 0, v[70:71]
	global_load_dwordx4 v[86:89], v[66:67], off nt
	global_load_dwordx4 v[82:85], v[66:67], off offset:256 nt
	global_load_dwordx4 v[78:81], v[68:69], off nt
	global_load_dwordx4 v[74:77], v[68:69], off offset:256 nt
	global_load_dwordx4 v[70:73], v[102:103], off nt
	s_nop 0
	global_load_dwordx4 v[66:69], v[102:103], off offset:256 nt
	s_waitcnt vmcnt(7)
	v_lshlrev_b32_e32 v102, 16, v92
	v_and_b32_e32 v103, 0xffff0000, v92
	v_lshlrev_b32_e32 v92, 16, v93
	v_and_b32_e32 v93, 0xffff0000, v93
	s_waitcnt vmcnt(6)
	v_lshlrev_b32_e32 v106, 16, v96
	v_and_b32_e32 v107, 0xffff0000, v96
	v_lshlrev_b32_e32 v96, 16, v97
	v_and_b32_e32 v97, 0xffff0000, v97
	v_lshlrev_b32_e32 v104, 16, v94
	v_and_b32_e32 v105, 0xffff0000, v94
	v_lshlrev_b32_e32 v94, 16, v95
	v_and_b32_e32 v95, 0xffff0000, v95
	v_lshlrev_b32_e32 v108, 16, v98
	v_and_b32_e32 v109, 0xffff0000, v98
	v_pk_add_f32 v[64:65], v[64:65], v[92:93]
	v_pk_add_f32 v[62:63], v[62:63], v[102:103]
	v_pk_add_f32 v[56:57], v[56:57], v[96:97]
	v_pk_add_f32 v[54:55], v[54:55], v[106:107]
	v_lshlrev_b32_e32 v98, 16, v99
	v_and_b32_e32 v99, 0xffff0000, v99
	v_pk_add_f32 v[60:61], v[60:61], v[94:95]
	v_pk_add_f32 v[58:59], v[58:59], v[104:105]
	v_pk_add_f32 v[94:95], v[50:51], v[108:109]
	v_cvt_pk_bf16_f32 v50, v62, v63
	v_cvt_pk_bf16_f32 v51, v64, v65
	v_mul_f32_e32 v63, v63, v63
	v_mul_f32_e32 v65, v65, v65
	v_mul_f32_e32 v96, v55, v55
	v_mul_f32_e32 v97, v57, v57
	v_pk_add_f32 v[92:93], v[52:53], v[98:99]
	v_cvt_pk_bf16_f32 v52, v58, v59
	v_cvt_pk_bf16_f32 v53, v60, v61
	v_mul_f32_e32 v59, v59, v59
	v_mul_f32_e32 v61, v61, v61
	v_mul_f32_e32 v98, v95, v95
	v_fmac_f32_e32 v63, v62, v62
	v_fmac_f32_e32 v65, v64, v64
	v_fmac_f32_e32 v96, v54, v54
	v_fmac_f32_e32 v97, v56, v56
	v_mul_f32_e32 v99, v93, v93
	v_fmac_f32_e32 v59, v58, v58
	v_fmac_f32_e32 v61, v60, v60
	v_fmac_f32_e32 v98, v94, v94
	v_add_f32_e32 v58, v63, v65
	v_add_f32_e32 v60, v96, v97
	v_fmac_f32_e32 v99, v92, v92
	v_add_f32_e32 v58, v59, v58
	v_add_f32_e32 v59, v98, v60
	v_add_f32_e32 v58, v61, v58
	v_add_f32_e32 v59, v99, v59
	v_add_f32_e32 v60, v58, v59
	v_mov_b32_e32 v61, v60
	s_nop 1
	v_permlane16_swap_b32_e32 v61, v60
	v_lshl_add_u64 v[58:59], s[14:15], 0, v[100:101]
	v_lshl_add_u64 v[58:59], v[170:171], 1, v[58:59]
	global_store_dwordx4 v[58:59], v[50:53], off
	s_waitcnt lgkmcnt(0)
	s_nop 0
	v_add_f32_e32 v50, v60, v61
	v_mov_b32_e32 v51, v50
	s_nop 1
	v_permlane32_swap_b32_e32 v51, v50
	v_cvt_pk_bf16_f32 v52, v54, v55
	v_cvt_pk_bf16_f32 v53, v56, v57
	v_cvt_pk_bf16_f32 v54, v94, v95
	v_cvt_pk_bf16_f32 v55, v92, v93
	global_store_dwordx4 v[58:59], v[52:55], off offset:256
	s_and_saveexec_b64 s[24:25], s[2:3]
	s_cbranch_execz .LBB0_2073
	v_lshl_add_u64 v[52:53], v[90:91], 2, s[16:17]
	s_waitcnt lgkmcnt(0)
	v_add_f32_e32 v50, v50, v51
	global_atomic_add_f32 v[52:53], v50, off
.LBB0_2073:
	s_or_b64 exec, exec, s[24:25]
	s_waitcnt vmcnt(7)
	v_lshlrev_b32_e32 v52, 16, v86
	v_and_b32_e32 v53, 0xffff0000, v86
	v_lshlrev_b32_e32 v54, 16, v87
	v_and_b32_e32 v55, 0xffff0000, v87
	v_lshlrev_b32_e32 v56, 16, v88
	v_and_b32_e32 v57, 0xffff0000, v88
	v_pk_add_f32 v[46:47], v[46:47], v[52:53]
	v_pk_add_f32 v[48:49], v[48:49], v[54:55]
	v_pk_add_f32 v[54:55], v[42:43], v[56:57]
	v_cvt_pk_bf16_f32 v42, v46, v47
	v_mul_f32_e32 v47, v47, v47
	v_fmac_f32_e32 v47, v46, v46
	v_mul_f32_e32 v46, v49, v49
	s_waitcnt vmcnt(6)
	v_lshlrev_b32_e32 v60, 16, v82
	v_and_b32_e32 v61, 0xffff0000, v82
	v_lshlrev_b32_e32 v62, 16, v83
	v_and_b32_e32 v63, 0xffff0000, v83
	v_fmac_f32_e32 v46, v48, v48
	v_lshlrev_b32_e32 v58, 16, v89
	v_and_b32_e32 v59, 0xffff0000, v89
	v_lshlrev_b32_e32 v64, 16, v84
	v_and_b32_e32 v65, 0xffff0000, v84
	v_add_f32_e32 v46, v47, v46
	v_mul_f32_e32 v47, v55, v55
	v_pk_add_f32 v[40:41], v[40:41], v[62:63]
	v_pk_add_f32 v[38:39], v[38:39], v[60:61]
	v_pk_add_f32 v[52:53], v[44:45], v[58:59]
	v_cvt_pk_bf16_f32 v43, v48, v49
	v_fmac_f32_e32 v47, v54, v54
	v_pk_add_f32 v[48:49], v[34:35], v[64:65]
	v_mul_f32_e32 v34, v39, v39
	v_mul_f32_e32 v35, v41, v41
	v_add_f32_e32 v46, v47, v46
	v_mul_f32_e32 v47, v53, v53
	v_fmac_f32_e32 v34, v38, v38
	v_fmac_f32_e32 v35, v40, v40
	v_lshlrev_b32_e32 v82, 16, v85
	v_and_b32_e32 v83, 0xffff0000, v85
	v_fmac_f32_e32 v47, v52, v52
	v_add_f32_e32 v34, v34, v35
	v_mul_f32_e32 v35, v49, v49
	v_cvt_pk_bf16_f32 v44, v54, v55
	v_cvt_pk_bf16_f32 v45, v52, v53
	v_add_f32_e32 v52, v47, v46
	v_pk_add_f32 v[46:47], v[36:37], v[82:83]
	v_fmac_f32_e32 v35, v48, v48
	v_add_f32_e32 v34, v35, v34
	v_mul_f32_e32 v35, v47, v47
	v_fmac_f32_e32 v35, v46, v46
	v_add_f32_e32 v34, v35, v34
	v_add_f32_e32 v37, v52, v34
	v_mov_b32_e32 v54, v37
	s_nop 1
	v_permlane16_swap_b32_e32 v54, v37
	v_or_b32_e32 v50, 16, v90
	s_waitcnt lgkmcnt(1)
	v_mov_b32_e32 v51, v91
	v_lshlrev_b64 v[84:85], 13, v[50:51]
	v_lshl_add_u64 v[34:35], s[14:15], 0, v[84:85]
	v_lshl_add_u64 v[52:53], v[170:171], 1, v[34:35]
	s_waitcnt lgkmcnt(0)
	v_add_f32_e32 v34, v37, v54
	v_mov_b32_e32 v35, v34
	s_nop 1
	v_permlane32_swap_b32_e32 v35, v34
	global_store_dwordx4 v[52:53], v[42:45], off
	v_cvt_pk_bf16_f32 v36, v38, v39
	v_cvt_pk_bf16_f32 v37, v40, v41
	v_cvt_pk_bf16_f32 v38, v48, v49
	v_cvt_pk_bf16_f32 v39, v46, v47
	global_store_dwordx4 v[52:53], v[36:39], off offset:256
	s_and_saveexec_b64 s[24:25], s[2:3]
	s_cbranch_execz .LBB0_2075
	v_lshl_add_u64 v[36:37], v[50:51], 2, s[16:17]
	s_waitcnt lgkmcnt(0)
	v_add_f32_e32 v34, v34, v35
	global_atomic_add_f32 v[36:37], v34, off
; __device__ __forceinline__ u32x4 pack8f(f32x4 a, f32x4 b) { u32x4 w; w.x = cvtpk(a[0], a[1]); w.y = cvtpk(a[2], a[3]); w.z = cvtpk(b[0], b[1]); w.w = cvtpk(b[2], b[3]); return w; }
; __device__ __forceinline__ void unpack8f(u32x4 w, f32x4& a, f32x4& b) { a = (f32x4){bflo(w.x), bfhi(w.x), bflo(w.y), bfhi(w.y)}; b = (f32x4){bflo(w.z), bfhi(w.z), bflo(w.w), bfhi(w.w)}; }
;     __device__ __forceinline__ void operator()(const f32x4 (&acc)[2][2][4][2], const Unit& u, int wr, int wc, int fr, int fq) const {
;     ...
;                 for (int m = 0; m < 4; ++m)
; #pragma unroll
;                     for (int bj = 0; bj < 2; ++bj) unpack8f(raw[m][bj], bq[m][bj][0], bq[m][bj][1]);
;     ...
;             for (int m = 0; m < 4; ++m) { const size_t row = row0 + m * 16;
;                 float sq = 0.f;
; #pragma unroll
;                 for (int bj = 0; bj < 2; ++bj) { const size_t o = row * 4096 + col + bj * HALF;
;                     const f32x4 v0 = bq[m][bj][0] + acc[ai][bj][m][0], v1 = bq[m][bj][1] + acc[ai][bj][m][1];
;                     *(u32x4*)(xb + o) = pack8f(v0, v1);
;                     sq += (v0[0] * v0[0] + v0[1] * v0[1]) + (v0[2] * v0[2] + v0[3] * v0[3]) + (v1[0] * v1[0] + v1[1] * v1[1]) + (v1[2] * v1[2] + v1[3] * v1[3]); }
;                 sq += __shfl_xor(sq, 16); sq += __shfl_xor(sq, 32);
;                 if (fq == 0) atomicAdd(ss + row, sq); }
.LBB0_2075:
	s_or_b64 exec, exec, s[24:25]
	s_waitcnt vmcnt(7)
	v_lshlrev_b32_e32 v36, 16, v78
	v_and_b32_e32 v37, 0xffff0000, v78
	v_lshlrev_b32_e32 v38, 16, v79
	v_and_b32_e32 v39, 0xffff0000, v79
	v_lshlrev_b32_e32 v40, 16, v80
	v_and_b32_e32 v41, 0xffff0000, v80
	v_pk_add_f32 v[30:31], v[30:31], v[36:37]
	v_pk_add_f32 v[32:33], v[32:33], v[38:39]
	v_pk_add_f32 v[38:39], v[26:27], v[40:41]
	v_cvt_pk_bf16_f32 v26, v30, v31
	v_mul_f32_e32 v31, v31, v31
	v_fmac_f32_e32 v31, v30, v30
	v_mul_f32_e32 v30, v33, v33
	s_waitcnt vmcnt(6)
	v_lshlrev_b32_e32 v44, 16, v74
	v_and_b32_e32 v45, 0xffff0000, v74
	v_lshlrev_b32_e32 v46, 16, v75
	v_and_b32_e32 v47, 0xffff0000, v75
	v_fmac_f32_e32 v30, v32, v32
	v_lshlrev_b32_e32 v42, 16, v81
	v_and_b32_e32 v43, 0xffff0000, v81
	v_lshlrev_b32_e32 v48, 16, v76
	v_and_b32_e32 v49, 0xffff0000, v76
	v_add_f32_e32 v30, v31, v30
	v_mul_f32_e32 v31, v39, v39
	v_pk_add_f32 v[24:25], v[24:25], v[46:47]
	v_pk_add_f32 v[22:23], v[22:23], v[44:45]
	v_pk_add_f32 v[36:37], v[28:29], v[42:43]
	v_cvt_pk_bf16_f32 v27, v32, v33
	v_fmac_f32_e32 v31, v38, v38
	v_pk_add_f32 v[32:33], v[18:19], v[48:49]
	v_mul_f32_e32 v18, v23, v23
	v_mul_f32_e32 v19, v25, v25
	v_add_f32_e32 v30, v31, v30
	v_mul_f32_e32 v31, v37, v37
	v_fmac_f32_e32 v18, v22, v22
	v_fmac_f32_e32 v19, v24, v24
	v_lshlrev_b32_e32 v50, 16, v77
	v_and_b32_e32 v51, 0xffff0000, v77
	v_fmac_f32_e32 v31, v36, v36
	v_add_f32_e32 v18, v18, v19
	v_mul_f32_e32 v19, v33, v33
	v_cvt_pk_bf16_f32 v28, v38, v39
	v_cvt_pk_bf16_f32 v29, v36, v37
	v_add_f32_e32 v36, v31, v30
	v_pk_add_f32 v[30:31], v[20:21], v[50:51]
	v_fmac_f32_e32 v19, v32, v32
	v_add_f32_e32 v18, v19, v18
	v_mul_f32_e32 v19, v31, v31
	v_fmac_f32_e32 v19, v30, v30
	v_add_f32_e32 v18, v19, v18
	v_add_f32_e32 v21, v36, v18
	v_mov_b32_e32 v38, v21
	s_nop 1
	v_permlane16_swap_b32_e32 v38, v21
	v_or_b32_e32 v34, 32, v90
	s_waitcnt lgkmcnt(1)
	v_mov_b32_e32 v35, v91
	v_lshlrev_b64 v[52:53], 13, v[34:35]
	v_lshl_add_u64 v[18:19], s[14:15], 0, v[52:53]
	v_lshl_add_u64 v[36:37], v[170:171], 1, v[18:19]
	s_waitcnt lgkmcnt(0)
	v_add_f32_e32 v18, v21, v38
	v_mov_b32_e32 v19, v18
	s_nop 1
	v_permlane32_swap_b32_e32 v19, v18
	global_store_dwordx4 v[36:37], v[26:29], off
	v_cvt_pk_bf16_f32 v20, v22, v23
	v_cvt_pk_bf16_f32 v21, v24, v25
	v_cvt_pk_bf16_f32 v22, v32, v33
	v_cvt_pk_bf16_f32 v23, v30, v31
	global_store_dwordx4 v[36:37], v[20:23], off offset:256
	s_and_saveexec_b64 s[24:25], s[2:3]
	s_cbranch_execz .LBB0_2077
	v_lshl_add_u64 v[20:21], v[34:35], 2, s[16:17]
	s_waitcnt lgkmcnt(0)
	v_add_f32_e32 v18, v18, v19
	global_atomic_add_f32 v[20:21], v18, off
.LBB0_2077:
	s_or_b64 exec, exec, s[24:25]
	s_waitcnt vmcnt(7)
	v_lshlrev_b32_e32 v18, 16, v70
	s_waitcnt lgkmcnt(0)
	v_and_b32_e32 v19, 0xffff0000, v70
	v_lshlrev_b32_e32 v20, 16, v71
	v_and_b32_e32 v21, 0xffff0000, v71
	v_lshlrev_b32_e32 v22, 16, v72
	v_and_b32_e32 v23, 0xffff0000, v72
	v_pk_add_f32 v[14:15], v[14:15], v[18:19]
	v_pk_add_f32 v[16:17], v[16:17], v[20:21]
	v_pk_add_f32 v[20:21], v[10:11], v[22:23]
	v_cvt_pk_bf16_f32 v10, v14, v15
	v_mul_f32_e32 v15, v15, v15
	v_fmac_f32_e32 v15, v14, v14
	v_mul_f32_e32 v14, v17, v17
	s_waitcnt vmcnt(6)
	v_lshlrev_b32_e32 v26, 16, v66
	v_and_b32_e32 v27, 0xffff0000, v66
	v_lshlrev_b32_e32 v28, 16, v67
	v_and_b32_e32 v29, 0xffff0000, v67
	v_fmac_f32_e32 v14, v16, v16
	v_lshlrev_b32_e32 v24, 16, v73
	v_and_b32_e32 v25, 0xffff0000, v73
	v_lshlrev_b32_e32 v30, 16, v68
	v_and_b32_e32 v31, 0xffff0000, v68
	v_add_f32_e32 v14, v15, v14
	v_mul_f32_e32 v15, v21, v21
	v_pk_add_f32 v[8:9], v[8:9], v[28:29]
	v_pk_add_f32 v[6:7], v[6:7], v[26:27]
	v_pk_add_f32 v[18:19], v[12:13], v[24:25]
	v_cvt_pk_bf16_f32 v11, v16, v17
	v_fmac_f32_e32 v15, v20, v20
	v_pk_add_f32 v[16:17], v[2:3], v[30:31]
	v_mul_f32_e32 v2, v7, v7
	v_mul_f32_e32 v3, v9, v9
	v_add_f32_e32 v14, v15, v14
	v_mul_f32_e32 v15, v19, v19
	v_fmac_f32_e32 v2, v6, v6
	v_fmac_f32_e32 v3, v8, v8
	v_lshlrev_b32_e32 v32, 16, v69
	v_and_b32_e32 v33, 0xffff0000, v69
	v_fmac_f32_e32 v15, v18, v18
	v_add_f32_e32 v2, v2, v3
	v_mul_f32_e32 v3, v17, v17
	v_cvt_pk_bf16_f32 v12, v20, v21
	v_cvt_pk_bf16_f32 v13, v18, v19
	v_add_f32_e32 v18, v15, v14
	v_pk_add_f32 v[14:15], v[4:5], v[32:33]
	v_fmac_f32_e32 v3, v16, v16
	v_add_f32_e32 v2, v3, v2
	v_mul_f32_e32 v3, v15, v15
	v_fmac_f32_e32 v3, v14, v14
	v_add_f32_e32 v2, v3, v2
	v_add_f32_e32 v5, v18, v2
	v_mov_b32_e32 v20, v5
	s_nop 1
	v_permlane16_swap_b32_e32 v20, v5
	v_or_b32_e32 v90, 48, v90
	v_lshlrev_b64 v[34:35], 13, v[90:91]
	v_lshl_add_u64 v[2:3], s[14:15], 0, v[34:35]
	v_lshl_add_u64 v[18:19], v[170:171], 1, v[2:3]
	s_waitcnt lgkmcnt(0)
	v_add_f32_e32 v2, v5, v20
	v_mov_b32_e32 v3, v2
	s_nop 1
	v_permlane32_swap_b32_e32 v3, v2
	global_store_dwordx4 v[18:19], v[10:13], off
	v_cvt_pk_bf16_f32 v4, v6, v7
	v_cvt_pk_bf16_f32 v5, v8, v9
	v_cvt_pk_bf16_f32 v6, v16, v17
	v_cvt_pk_bf16_f32 v7, v14, v15
	global_store_dwordx4 v[18:19], v[4:7], off offset:256
	s_and_saveexec_b64 s[24:25], s[2:3]
	s_cbranch_execz .LBB0_2079
	v_lshl_add_u64 v[4:5], v[90:91], 2, s[16:17]
	s_waitcnt lgkmcnt(0)
	v_add_f32_e32 v2, v2, v3
	global_atomic_add_f32 v[4:5], v2, off
